# GEMM loops: s_setprio 1 issued before the pre-MFMA barrier instead of after it
# speedup vs baseline: 1.0101x; 1.0010x over previous
; #define PG8_STAGE(bufoff, gbase, voff) do { _Pragma("unroll") for (int _i = 0; _i < 2; ++_i) \
;         __builtin_amdgcn_global_load_lds((const unsigned*)((const char*)(gbase) + (voff)[_i]), (PG8_LAS unsigned*)(lds + (bufoff) + ldsw + _i * 8192), 16, 0, 0); } while (0)
; #define PG8_LDA(dst, b, h) do { _Pragma("unroll") for (int m = 0; m < 4; ++m) _Pragma("unroll") for (int k = 0; k < 2; ++k) dst[m][k] = *(const PG8_LAS bf16x8*)(lds + PG8_SA(b, h) + aoff + m * 2048 + k * 1024); } while (0)
; #define PG8_LDB(dst, b, h) do { _Pragma("unroll") for (int n = 0; n < 2; ++n) _Pragma("unroll") for (int k = 0; k < 2; ++k) dst[n][k] = *(const PG8_LAS bf16x8*)(lds + PG8_SB(b, h) + boff + n * 2048 + k * 1024); } while (0)
; #define PG8_MMA(ai, bj, At, Bt) do { __builtin_amdgcn_s_setprio(1); _Pragma("unroll") for (int m = 0; m < 4; ++m) _Pragma("unroll") for (int n = 0; n < 2; ++n) _Pragma("unroll") for (int k = 0; k < 2; ++k) \
;         acc[ai][bj][m][n] = __builtin_amdgcn_mfma_f32_16x16x32_bf16(Bt[n][k], At[m][k], acc[ai][bj][m][n], 0, 0, 0); __builtin_amdgcn_s_setprio(0); } while (0)
; #define PG8_WAIT_V(n) asm volatile("s_waitcnt vmcnt(" #n ")" ::: "memory")
; #define PG8_BAR __builtin_amdgcn_s_barrier()
; template <class Epi, class Sched, bool ALIGN_EPI = false, bool SP2 = false>
; __device__ __forceinline__ void gemm_phase(PG8_LAS unsigned char* lds, const Gemm g, const Sched& S, const Epi& E) {
;     ...
;         for (int t = 0; t < nt; t += 2) {
;             const bool last = (t == nt - 2);
;             const char* a1 = cA + (size_t)(t + 1) * kstep;
;             const char* a2 = last ? nA : cA + (size_t)(t + 2) * kstep; const char* b2 = last ? nB : cB + (size_t)(t + 2) * kstep;
;             const char* a3 = a2 + kstep; const char* b3 = b2 + kstep;
;             if (last && has_next) S.a_ready(nxt);
;             if constexpr (SP2) {
;             PG8_LDB(B0, 0, 0); PG8_LDB(B1, 0, 1); PG8_SCHED; PG8_LDA(At, 0, 0); PG8_STAGE(PG8_SA(1, 1), a1 + hstep, voffA);
;             PG8_WAIT_V(8); PG8_WAIT_L(0); PG8_BAR; PG8_MMA(0, 0, At, B0); PG8_MMA(0, 1, At, B1); PG8_BAR; PG8_SCHED;
;             PG8_LDA(At, 0, 1); PG8_STAGE(PG8_SB(0, 0), b2, voffB); PG8_STAGE(PG8_SB(0, 1), b2 + hstep, voffB); PG8_STAGE(PG8_SA(0, 0), a2, voffA);
;             PG8_WAIT_V(8); PG8_WAIT_L(0); PG8_BAR; PG8_MMA(1, 0, At, B0); PG8_MMA(1, 1, At, B1); PG8_BAR; PG8_SCHED;
.LBB0_216:
	ds_read_b128 v[144:147], v151
	ds_read_b128 v[154:157], v151 offset:1024
	ds_read_b128 v[158:161], v151 offset:2048
	ds_read_b128 v[162:165], v151 offset:3072
	ds_read_b128 v[166:169], v152
	ds_read_b128 v[170:173], v152 offset:1024
	ds_read_b128 v[176:179], v152 offset:2048
	ds_read_b128 v[180:183], v152 offset:3072
	s_add_u32 s28, s26, 0xfff80080
	s_addc_u32 s29, s27, -1
	s_cmp_eq_u32 s85, 28
	s_cselect_b32 s31, s19, s29
	s_cselect_b32 s30, s73, s28
	s_cselect_b32 s29, s17, s84
	s_cselect_b32 s28, s76, s77
	v_lshl_add_u64 v[216:217], s[26:27], 0, v[136:137]
	s_add_i32 m0, s25, 0xc000
	ds_read_b128 v[184:187], v153
	ds_read_b128 v[188:191], v153 offset:1024
	ds_read_b128 v[192:195], v153 offset:2048
	ds_read_b128 v[196:199], v153 offset:3072
	ds_read_b128 v[200:203], v153 offset:4096
	ds_read_b128 v[204:207], v153 offset:5120
	ds_read_b128 v[208:211], v153 offset:6144
	ds_read_b128 v[212:215], v153 offset:7168
	global_load_lds_dwordx4 v[216:217], off
	v_lshl_add_u64 v[216:217], s[26:27], 0, v[138:139]
	s_add_i32 m0, s25, 0xe000
	s_nop 0
	global_load_lds_dwordx4 v[216:217], off
	s_waitcnt vmcnt(8)
	s_waitcnt lgkmcnt(0)
	s_setprio 1
	s_barrier
	s_waitcnt lgkmcnt(0)
	v_mfma_f32_16x16x32_bf16 v[124:127], v[144:147], v[184:187], v[124:127]
	v_mfma_f32_16x16x32_bf16 v[120:123], v[158:161], v[184:187], v[120:123]
	v_mfma_f32_16x16x32_bf16 v[116:119], v[144:147], v[192:195], v[116:119]
	v_mfma_f32_16x16x32_bf16 v[108:111], v[158:161], v[192:195], v[108:111]
	v_mfma_f32_16x16x32_bf16 v[100:103], v[144:147], v[200:203], v[100:103]
	v_mfma_f32_16x16x32_bf16 v[92:95], v[158:161], v[200:203], v[92:95]
	v_mfma_f32_16x16x32_bf16 v[84:87], v[144:147], v[208:211], v[84:87]
	v_mfma_f32_16x16x32_bf16 v[76:79], v[158:161], v[208:211], v[76:79]
	v_mfma_f32_16x16x32_bf16 v[124:127], v[154:157], v[188:191], v[124:127]
	v_mfma_f32_16x16x32_bf16 v[120:123], v[162:165], v[188:191], v[120:123]
	v_mfma_f32_16x16x32_bf16 v[116:119], v[154:157], v[196:199], v[116:119]
	v_mfma_f32_16x16x32_bf16 v[108:111], v[162:165], v[196:199], v[108:111]
	v_mfma_f32_16x16x32_bf16 v[100:103], v[154:157], v[204:207], v[100:103]
	v_mfma_f32_16x16x32_bf16 v[92:95], v[162:165], v[204:207], v[92:95]
	v_mfma_f32_16x16x32_bf16 v[84:87], v[154:157], v[212:215], v[84:87]
	v_mfma_f32_16x16x32_bf16 v[76:79], v[162:165], v[212:215], v[76:79]
	s_setprio 0
	s_setprio 1
	v_mfma_f32_16x16x32_bf16 v[112:115], v[166:169], v[184:187], v[112:115]
	v_mfma_f32_16x16x32_bf16 v[104:107], v[176:179], v[184:187], v[104:107]
	v_mfma_f32_16x16x32_bf16 v[96:99], v[166:169], v[192:195], v[96:99]
	v_mfma_f32_16x16x32_bf16 v[88:91], v[176:179], v[192:195], v[88:91]
	v_mfma_f32_16x16x32_bf16 v[80:83], v[166:169], v[200:203], v[80:83]
	v_mfma_f32_16x16x32_bf16 v[72:75], v[176:179], v[200:203], v[72:75]
	v_mfma_f32_16x16x32_bf16 v[68:71], v[166:169], v[208:211], v[68:71]
	v_mfma_f32_16x16x32_bf16 v[64:67], v[176:179], v[208:211], v[64:67]
	v_mfma_f32_16x16x32_bf16 v[112:115], v[170:173], v[188:191], v[112:115]
	v_mfma_f32_16x16x32_bf16 v[104:107], v[180:183], v[188:191], v[104:107]
	v_mfma_f32_16x16x32_bf16 v[96:99], v[170:173], v[196:199], v[96:99]
	v_mfma_f32_16x16x32_bf16 v[88:91], v[180:183], v[196:199], v[88:91]
	v_mfma_f32_16x16x32_bf16 v[80:83], v[170:173], v[204:207], v[80:83]
	v_mfma_f32_16x16x32_bf16 v[72:75], v[180:183], v[204:207], v[72:75]
	v_mfma_f32_16x16x32_bf16 v[68:71], v[170:173], v[212:215], v[68:71]
	v_mfma_f32_16x16x32_bf16 v[64:67], v[180:183], v[212:215], v[64:67]
	s_setprio 0
	s_barrier
	s_add_i32 s44, s56, s41
	v_lshl_add_u64 v[216:217], s[28:29], 0, v[130:131]
	s_mov_b32 m0, s44
	ds_read_b128 v[184:187], v153 offset:16384
	ds_read_b128 v[188:191], v153 offset:17408
	ds_read_b128 v[192:195], v153 offset:18432
	ds_read_b128 v[196:199], v153 offset:19456
	ds_read_b128 v[200:203], v153 offset:20480
	ds_read_b128 v[204:207], v153 offset:21504
	ds_read_b128 v[208:211], v153 offset:22528
	ds_read_b128 v[212:215], v153 offset:23552
	global_load_lds_dwordx4 v[216:217], off
	s_add_i32 m0, s44, 0x2000
	s_add_u32 s86, s28, 0x80000
	v_lshl_add_u64 v[218:219], s[28:29], 0, v[134:135]
	s_addc_u32 s87, s29, 0
	s_add_i32 s44, s57, s41
	global_load_lds_dwordx4 v[218:219], off
	v_lshl_add_u64 v[220:221], s[86:87], 0, v[130:131]
	s_mov_b32 m0, s44
	v_lshl_add_u64 v[222:223], s[30:31], 0, v[132:133]
	global_load_lds_dwordx4 v[220:221], off
	v_lshl_add_u64 v[220:221], s[86:87], 0, v[134:135]
	s_add_i32 m0, s44, 0x2000
	s_nop 0
	global_load_lds_dwordx4 v[220:221], off
	v_lshl_add_u64 v[220:221], s[30:31], 0, v[128:129]
	s_mov_b32 m0, s25
	s_nop 0
	global_load_lds_dwordx4 v[220:221], off
	s_mov_b32 m0, s46
	s_nop 0
	global_load_lds_dwordx4 v[222:223], off
	s_waitcnt vmcnt(8)
	s_waitcnt lgkmcnt(0)
	s_setprio 1
	s_barrier
; #define PG8_STAGE(bufoff, gbase, voff) do { _Pragma("unroll") for (int _i = 0; _i < 2; ++_i) \
;         __builtin_amdgcn_global_load_lds((const unsigned*)((const char*)(gbase) + (voff)[_i]), (PG8_LAS unsigned*)(lds + (bufoff) + ldsw + _i * 8192), 16, 0, 0); } while (0)
; #define PG8_LDA(dst, b, h) do { _Pragma("unroll") for (int m = 0; m < 4; ++m) _Pragma("unroll") for (int k = 0; k < 2; ++k) dst[m][k] = *(const PG8_LAS bf16x8*)(lds + PG8_SA(b, h) + aoff + m * 2048 + k * 1024); } while (0)
; #define PG8_LDB(dst, b, h) do { _Pragma("unroll") for (int n = 0; n < 2; ++n) _Pragma("unroll") for (int k = 0; k < 2; ++k) dst[n][k] = *(const PG8_LAS bf16x8*)(lds + PG8_SB(b, h) + boff + n * 2048 + k * 1024); } while (0)
; #define PG8_MMA(ai, bj, At, Bt) do { __builtin_amdgcn_s_setprio(1); _Pragma("unroll") for (int m = 0; m < 4; ++m) _Pragma("unroll") for (int n = 0; n < 2; ++n) _Pragma("unroll") for (int k = 0; k < 2; ++k) \
;         acc[ai][bj][m][n] = __builtin_amdgcn_mfma_f32_16x16x32_bf16(Bt[n][k], At[m][k], acc[ai][bj][m][n], 0, 0, 0); __builtin_amdgcn_s_setprio(0); } while (0)
; #define PG8_WAIT_V(n) asm volatile("s_waitcnt vmcnt(" #n ")" ::: "memory")
; #define PG8_WAIT_L(n) asm volatile("s_waitcnt lgkmcnt(" #n ")" ::: "memory")
; #define PG8_BAR __builtin_amdgcn_s_barrier()
; #define PG8_SCHED __builtin_amdgcn_sched_barrier(0)
; template <class Epi, class Sched, bool ALIGN_EPI = false, bool SP2 = false>
; __device__ __forceinline__ void gemm_phase(PG8_LAS unsigned char* lds, const Gemm g, const Sched& S, const Epi& E) {
;     ...
;             PG8_WAIT_V(8); PG8_WAIT_L(0); PG8_BAR; PG8_MMA(1, 0, At, B0); PG8_MMA(1, 1, At, B1); PG8_BAR; PG8_SCHED;
;             PG8_LDB(B0, 1, 0); PG8_LDB(B1, 1, 1); PG8_SCHED; PG8_LDA(At, 1, 0); PG8_STAGE(PG8_SA(0, 1), a2 + hstep, voffA);
;             PG8_WAIT_V(8); PG8_WAIT_L(0); PG8_BAR; PG8_MMA(0, 0, At, B0); PG8_MMA(0, 1, At, B1); PG8_BAR; PG8_SCHED;
	s_waitcnt lgkmcnt(0)
	v_mfma_f32_16x16x32_bf16 v[60:63], v[144:147], v[184:187], v[60:63]
	v_mfma_f32_16x16x32_bf16 v[56:59], v[158:161], v[184:187], v[56:59]
	v_mfma_f32_16x16x32_bf16 v[52:55], v[144:147], v[192:195], v[52:55]
	v_mfma_f32_16x16x32_bf16 v[44:47], v[158:161], v[192:195], v[44:47]
	v_mfma_f32_16x16x32_bf16 v[36:39], v[144:147], v[200:203], v[36:39]
	v_mfma_f32_16x16x32_bf16 v[28:31], v[158:161], v[200:203], v[28:31]
	v_mfma_f32_16x16x32_bf16 v[20:23], v[144:147], v[208:211], v[20:23]
	v_mfma_f32_16x16x32_bf16 v[12:15], v[158:161], v[208:211], v[12:15]
	v_mfma_f32_16x16x32_bf16 v[60:63], v[154:157], v[188:191], v[60:63]
	v_mfma_f32_16x16x32_bf16 v[56:59], v[162:165], v[188:191], v[56:59]
	v_mfma_f32_16x16x32_bf16 v[52:55], v[154:157], v[196:199], v[52:55]
	v_mfma_f32_16x16x32_bf16 v[44:47], v[162:165], v[196:199], v[44:47]
	v_mfma_f32_16x16x32_bf16 v[36:39], v[154:157], v[204:207], v[36:39]
	v_mfma_f32_16x16x32_bf16 v[28:31], v[162:165], v[204:207], v[28:31]
	v_mfma_f32_16x16x32_bf16 v[20:23], v[154:157], v[212:215], v[20:23]
	v_mfma_f32_16x16x32_bf16 v[12:15], v[162:165], v[212:215], v[12:15]
	s_setprio 0
	s_setprio 1
	v_mfma_f32_16x16x32_bf16 v[48:51], v[166:169], v[184:187], v[48:51]
	v_mfma_f32_16x16x32_bf16 v[40:43], v[176:179], v[184:187], v[40:43]
	v_mfma_f32_16x16x32_bf16 v[32:35], v[166:169], v[192:195], v[32:35]
	v_mfma_f32_16x16x32_bf16 v[24:27], v[176:179], v[192:195], v[24:27]
	v_mfma_f32_16x16x32_bf16 v[16:19], v[166:169], v[200:203], v[16:19]
	v_mfma_f32_16x16x32_bf16 v[8:11], v[176:179], v[200:203], v[8:11]
	v_mfma_f32_16x16x32_bf16 v[4:7], v[166:169], v[208:211], v[4:7]
	v_mfma_f32_16x16x32_bf16 v[0:3], v[176:179], v[208:211], v[0:3]
	v_mfma_f32_16x16x32_bf16 v[48:51], v[170:173], v[188:191], v[48:51]
	v_mfma_f32_16x16x32_bf16 v[40:43], v[180:183], v[188:191], v[40:43]
	v_mfma_f32_16x16x32_bf16 v[32:35], v[170:173], v[196:199], v[32:35]
	v_mfma_f32_16x16x32_bf16 v[24:27], v[180:183], v[196:199], v[24:27]
	v_mfma_f32_16x16x32_bf16 v[16:19], v[170:173], v[204:207], v[16:19]
	v_mfma_f32_16x16x32_bf16 v[8:11], v[180:183], v[204:207], v[8:11]
	v_mfma_f32_16x16x32_bf16 v[4:7], v[170:173], v[212:215], v[4:7]
	v_mfma_f32_16x16x32_bf16 v[0:3], v[180:183], v[212:215], v[0:3]
	s_setprio 0
	s_barrier
	s_add_i32 s44, 0, 0x18000
	s_add_i32 s45, 0, 0x1c000
	v_add_u32_e32 v162, s44, v149
	v_add_u32_e32 v180, s45, v149
	ds_read_b128 v[144:147], v162
	ds_read_b128 v[154:157], v162 offset:1024
	ds_read_b128 v[158:161], v162 offset:2048
	ds_read_b128 v[162:165], v162 offset:3072
	ds_read_b128 v[166:169], v180
	ds_read_b128 v[170:173], v180 offset:1024
	ds_read_b128 v[176:179], v180 offset:2048
	ds_read_b128 v[180:183], v180 offset:3072
	s_add_u32 s30, s30, 0x80000
	s_addc_u32 s31, s31, 0
	s_mov_b32 m0, s47
	v_lshl_add_u64 v[224:225], s[30:31], 0, v[128:129]
	ds_read_b128 v[184:187], v153 offset:32768
	ds_read_b128 v[188:191], v153 offset:33792
	ds_read_b128 v[192:195], v153 offset:34816
	ds_read_b128 v[196:199], v153 offset:35840
	ds_read_b128 v[200:203], v153 offset:36864
	ds_read_b128 v[204:207], v153 offset:37888
	ds_read_b128 v[208:211], v153 offset:38912
	ds_read_b128 v[212:215], v153 offset:39936
	global_load_lds_dwordx4 v[224:225], off
	v_lshl_add_u64 v[224:225], s[30:31], 0, v[132:133]
	s_mov_b32 m0, s48
	s_nop 0
	global_load_lds_dwordx4 v[224:225], off
	s_waitcnt vmcnt(8)
	s_waitcnt lgkmcnt(0)
	s_setprio 1
	s_barrier
	s_waitcnt lgkmcnt(0)
	v_mfma_f32_16x16x32_bf16 v[124:127], v[144:147], v[184:187], v[124:127]
	v_mfma_f32_16x16x32_bf16 v[120:123], v[158:161], v[184:187], v[120:123]
	v_mfma_f32_16x16x32_bf16 v[116:119], v[144:147], v[192:195], v[116:119]
	v_mfma_f32_16x16x32_bf16 v[108:111], v[158:161], v[192:195], v[108:111]
	v_mfma_f32_16x16x32_bf16 v[100:103], v[144:147], v[200:203], v[100:103]
	v_mfma_f32_16x16x32_bf16 v[92:95], v[158:161], v[200:203], v[92:95]
	v_mfma_f32_16x16x32_bf16 v[84:87], v[144:147], v[208:211], v[84:87]
	v_mfma_f32_16x16x32_bf16 v[76:79], v[158:161], v[208:211], v[76:79]
	v_mfma_f32_16x16x32_bf16 v[124:127], v[154:157], v[188:191], v[124:127]
	v_mfma_f32_16x16x32_bf16 v[120:123], v[162:165], v[188:191], v[120:123]
	v_mfma_f32_16x16x32_bf16 v[116:119], v[154:157], v[196:199], v[116:119]
	v_mfma_f32_16x16x32_bf16 v[108:111], v[162:165], v[196:199], v[108:111]
	v_mfma_f32_16x16x32_bf16 v[100:103], v[154:157], v[204:207], v[100:103]
	v_mfma_f32_16x16x32_bf16 v[92:95], v[162:165], v[204:207], v[92:95]
	v_mfma_f32_16x16x32_bf16 v[84:87], v[154:157], v[212:215], v[84:87]
	v_mfma_f32_16x16x32_bf16 v[76:79], v[162:165], v[212:215], v[76:79]
	s_setprio 0
	s_setprio 1
	v_mfma_f32_16x16x32_bf16 v[112:115], v[166:169], v[184:187], v[112:115]
	v_mfma_f32_16x16x32_bf16 v[104:107], v[176:179], v[184:187], v[104:107]
	v_mfma_f32_16x16x32_bf16 v[96:99], v[166:169], v[192:195], v[96:99]
	v_mfma_f32_16x16x32_bf16 v[88:91], v[176:179], v[192:195], v[88:91]
	v_mfma_f32_16x16x32_bf16 v[80:83], v[166:169], v[200:203], v[80:83]
	v_mfma_f32_16x16x32_bf16 v[72:75], v[176:179], v[200:203], v[72:75]
	v_mfma_f32_16x16x32_bf16 v[68:71], v[166:169], v[208:211], v[68:71]
	v_mfma_f32_16x16x32_bf16 v[64:67], v[176:179], v[208:211], v[64:67]
	v_mfma_f32_16x16x32_bf16 v[112:115], v[170:173], v[188:191], v[112:115]
	v_mfma_f32_16x16x32_bf16 v[104:107], v[180:183], v[188:191], v[104:107]
	v_mfma_f32_16x16x32_bf16 v[96:99], v[170:173], v[196:199], v[96:99]
	v_mfma_f32_16x16x32_bf16 v[88:91], v[180:183], v[196:199], v[88:91]
	v_mfma_f32_16x16x32_bf16 v[80:83], v[170:173], v[204:207], v[80:83]
	v_mfma_f32_16x16x32_bf16 v[72:75], v[180:183], v[204:207], v[72:75]
	v_mfma_f32_16x16x32_bf16 v[68:71], v[170:173], v[212:215], v[68:71]
	v_mfma_f32_16x16x32_bf16 v[64:67], v[180:183], v[212:215], v[64:67]
	s_setprio 0
	s_barrier
; #define PG8_STAGE(bufoff, gbase, voff) do { _Pragma("unroll") for (int _i = 0; _i < 2; ++_i) \
;         __builtin_amdgcn_global_load_lds((const unsigned*)((const char*)(gbase) + (voff)[_i]), (PG8_LAS unsigned*)(lds + (bufoff) + ldsw + _i * 8192), 16, 0, 0); } while (0)
; #define PG8_LDA(dst, b, h) do { _Pragma("unroll") for (int m = 0; m < 4; ++m) _Pragma("unroll") for (int k = 0; k < 2; ++k) dst[m][k] = *(const PG8_LAS bf16x8*)(lds + PG8_SA(b, h) + aoff + m * 2048 + k * 1024); } while (0)
; #define PG8_MMA(ai, bj, At, Bt) do { __builtin_amdgcn_s_setprio(1); _Pragma("unroll") for (int m = 0; m < 4; ++m) _Pragma("unroll") for (int n = 0; n < 2; ++n) _Pragma("unroll") for (int k = 0; k < 2; ++k) \
;         acc[ai][bj][m][n] = __builtin_amdgcn_mfma_f32_16x16x32_bf16(Bt[n][k], At[m][k], acc[ai][bj][m][n], 0, 0, 0); __builtin_amdgcn_s_setprio(0); } while (0)
; #define PG8_WAIT_V(n) asm volatile("s_waitcnt vmcnt(" #n ")" ::: "memory")
; #define PG8_WAIT_L(n) asm volatile("s_waitcnt lgkmcnt(" #n ")" ::: "memory")
; #define PG8_BAR __builtin_amdgcn_s_barrier()
; #define PG8_SCHED __builtin_amdgcn_sched_barrier(0)
; template <class Epi, class Sched, bool ALIGN_EPI = false, bool SP2 = false>
; __device__ __forceinline__ void gemm_phase(PG8_LAS unsigned char* lds, const Gemm g, const Sched& S, const Epi& E) {
;     ...
;         for (int t = 0; t < nt; t += 2) {
;             const bool last = (t == nt - 2);
;             const char* a1 = cA + (size_t)(t + 1) * kstep;
;             const char* a2 = last ? nA : cA + (size_t)(t + 2) * kstep; const char* b2 = last ? nB : cB + (size_t)(t + 2) * kstep;
;     ...
;             PG8_LDA(At, 1, 1); PG8_STAGE(PG8_SB(1, 0), b3, voffB); PG8_STAGE(PG8_SB(1, 1), b3 + hstep, voffB); PG8_STAGE(PG8_SA(1, 0), a3, voffA);
;             PG8_WAIT_V(8); PG8_WAIT_L(0); PG8_BAR; PG8_MMA(1, 0, At, B0); PG8_MMA(1, 1, At, B1); PG8_BAR; PG8_SCHED;
	s_add_i32 s30, s44, s41
	v_lshl_add_u64 v[216:217], v[216:217], 0, s[12:13]
	s_mov_b32 m0, s30
	ds_read_b128 v[184:187], v153 offset:49152
	ds_read_b128 v[188:191], v153 offset:50176
	ds_read_b128 v[192:195], v153 offset:51200
	ds_read_b128 v[196:199], v153 offset:52224
	ds_read_b128 v[200:203], v153 offset:53248
	ds_read_b128 v[204:207], v153 offset:54272
	ds_read_b128 v[208:211], v153 offset:55296
	ds_read_b128 v[212:215], v153 offset:56320
	global_load_lds_dwordx4 v[216:217], off
	s_add_i32 m0, s30, 0x2000
	s_add_u32 s28, s28, 0x80080
	v_lshl_add_u64 v[216:217], v[218:219], 0, s[12:13]
	s_addc_u32 s29, s29, 0
	s_add_i32 s30, s45, s41
	global_load_lds_dwordx4 v[216:217], off
	v_lshl_add_u64 v[216:217], s[28:29], 0, v[130:131]
	s_mov_b32 m0, s30
	s_nop 0
	global_load_lds_dwordx4 v[216:217], off
	v_lshl_add_u64 v[216:217], s[28:29], 0, v[134:135]
	s_add_i32 m0, s30, 0x2000
	s_nop 0
	global_load_lds_dwordx4 v[216:217], off
	v_lshl_add_u64 v[216:217], v[220:221], 0, s[12:13]
	s_mov_b32 m0, s52
	s_nop 0
	global_load_lds_dwordx4 v[216:217], off
	v_lshl_add_u64 v[216:217], v[222:223], 0, s[12:13]
	s_mov_b32 m0, s53
	s_nop 0
	global_load_lds_dwordx4 v[216:217], off
	s_waitcnt vmcnt(8)
	s_waitcnt lgkmcnt(0)
	s_setprio 1
	s_barrier
	s_waitcnt lgkmcnt(0)
	v_mfma_f32_16x16x32_bf16 v[60:63], v[144:147], v[184:187], v[60:63]
	v_mfma_f32_16x16x32_bf16 v[56:59], v[158:161], v[184:187], v[56:59]
	v_mfma_f32_16x16x32_bf16 v[52:55], v[144:147], v[192:195], v[52:55]
	v_mfma_f32_16x16x32_bf16 v[44:47], v[158:161], v[192:195], v[44:47]
	v_mfma_f32_16x16x32_bf16 v[36:39], v[144:147], v[200:203], v[36:39]
	v_mfma_f32_16x16x32_bf16 v[28:31], v[158:161], v[200:203], v[28:31]
	v_mfma_f32_16x16x32_bf16 v[20:23], v[144:147], v[208:211], v[20:23]
	v_mfma_f32_16x16x32_bf16 v[12:15], v[158:161], v[208:211], v[12:15]
	v_mfma_f32_16x16x32_bf16 v[60:63], v[154:157], v[188:191], v[60:63]
	v_mfma_f32_16x16x32_bf16 v[56:59], v[162:165], v[188:191], v[56:59]
	v_mfma_f32_16x16x32_bf16 v[52:55], v[154:157], v[196:199], v[52:55]
	v_mfma_f32_16x16x32_bf16 v[44:47], v[162:165], v[196:199], v[44:47]
	v_mfma_f32_16x16x32_bf16 v[36:39], v[154:157], v[204:207], v[36:39]
	v_mfma_f32_16x16x32_bf16 v[28:31], v[162:165], v[204:207], v[28:31]
	v_mfma_f32_16x16x32_bf16 v[20:23], v[154:157], v[212:215], v[20:23]
	v_mfma_f32_16x16x32_bf16 v[12:15], v[162:165], v[212:215], v[12:15]
	s_setprio 0
	s_setprio 1
	v_mfma_f32_16x16x32_bf16 v[48:51], v[166:169], v[184:187], v[48:51]
	v_mfma_f32_16x16x32_bf16 v[40:43], v[176:179], v[184:187], v[40:43]
	v_mfma_f32_16x16x32_bf16 v[32:35], v[166:169], v[192:195], v[32:35]
	v_mfma_f32_16x16x32_bf16 v[24:27], v[176:179], v[192:195], v[24:27]
	v_mfma_f32_16x16x32_bf16 v[16:19], v[166:169], v[200:203], v[16:19]
	v_mfma_f32_16x16x32_bf16 v[8:11], v[176:179], v[200:203], v[8:11]
	v_mfma_f32_16x16x32_bf16 v[4:7], v[166:169], v[208:211], v[4:7]
	v_mfma_f32_16x16x32_bf16 v[0:3], v[176:179], v[208:211], v[0:3]
	v_mfma_f32_16x16x32_bf16 v[48:51], v[170:173], v[188:191], v[48:51]
	v_mfma_f32_16x16x32_bf16 v[40:43], v[180:183], v[188:191], v[40:43]
	v_mfma_f32_16x16x32_bf16 v[32:35], v[170:173], v[196:199], v[32:35]
	v_mfma_f32_16x16x32_bf16 v[24:27], v[180:183], v[196:199], v[24:27]
	v_mfma_f32_16x16x32_bf16 v[16:19], v[170:173], v[204:207], v[16:19]
	v_mfma_f32_16x16x32_bf16 v[8:11], v[180:183], v[204:207], v[8:11]
	v_mfma_f32_16x16x32_bf16 v[4:7], v[170:173], v[212:215], v[4:7]
	v_mfma_f32_16x16x32_bf16 v[0:3], v[180:183], v[212:215], v[0:3]
	s_setprio 0
	s_barrier
	s_add_i32 s85, s85, 2
	s_add_u32 s26, s26, 0x100
	s_addc_u32 s27, s27, 0
	s_add_u32 s77, s77, 0x100
	s_addc_u32 s84, s84, 0
	s_cmp_gt_u32 s85, 29
	s_cbranch_scc0 .LBB0_216
	s_and_b64 vcc, exec, s[14:15]
	s_cbranch_vccz .LBB0_219
	s_barrier

; #define PG8_STAGE(bufoff, gbase, voff) do { _Pragma("unroll") for (int _i = 0; _i < 2; ++_i) \
;         __builtin_amdgcn_global_load_lds((const unsigned*)((const char*)(gbase) + (voff)[_i]), (PG8_LAS unsigned*)(lds + (bufoff) + ldsw + _i * 8192), 16, 0, 0); } while (0)
; #define PG8_LDA(dst, b, h) do { _Pragma("unroll") for (int m = 0; m < 4; ++m) _Pragma("unroll") for (int k = 0; k < 2; ++k) dst[m][k] = *(const PG8_LAS bf16x8*)(lds + PG8_SA(b, h) + aoff + m * 2048 + k * 1024); } while (0)
; #define PG8_LDB(dst, b, h) do { _Pragma("unroll") for (int n = 0; n < 2; ++n) _Pragma("unroll") for (int k = 0; k < 2; ++k) dst[n][k] = *(const PG8_LAS bf16x8*)(lds + PG8_SB(b, h) + boff + n * 2048 + k * 1024); } while (0)
; #define PG8_MMA(ai, bj, At, Bt) do { __builtin_amdgcn_s_setprio(1); _Pragma("unroll") for (int m = 0; m < 4; ++m) _Pragma("unroll") for (int n = 0; n < 2; ++n) _Pragma("unroll") for (int k = 0; k < 2; ++k) \
;         acc[ai][bj][m][n] = __builtin_amdgcn_mfma_f32_16x16x32_bf16(Bt[n][k], At[m][k], acc[ai][bj][m][n], 0, 0, 0); __builtin_amdgcn_s_setprio(0); } while (0)
; #define PG8_WAIT_V(n) asm volatile("s_waitcnt vmcnt(" #n ")" ::: "memory")
; #define PG8_BAR __builtin_amdgcn_s_barrier()
; template <class Epi, class Sched, bool ALIGN_EPI = false, bool SP2 = false>
; __device__ __forceinline__ void gemm_phase(PG8_LAS unsigned char* lds, const Gemm g, const Sched& S, const Epi& E) {
;     ...
;         for (int t = 0; t < nt; t += 2) {
;             const bool last = (t == nt - 2);
;             const char* a1 = cA + (size_t)(t + 1) * kstep;
;             const char* a2 = last ? nA : cA + (size_t)(t + 2) * kstep; const char* b2 = last ? nB : cB + (size_t)(t + 2) * kstep;
;             const char* a3 = a2 + kstep; const char* b3 = b2 + kstep;
;             if (last && has_next) S.a_ready(nxt);
;             if constexpr (SP2) {
;             PG8_LDB(B0, 0, 0); PG8_LDB(B1, 0, 1); PG8_SCHED; PG8_LDA(At, 0, 0); PG8_STAGE(PG8_SA(1, 1), a1 + hstep, voffA);
;             PG8_WAIT_V(8); PG8_WAIT_L(0); PG8_BAR; PG8_MMA(0, 0, At, B0); PG8_MMA(0, 1, At, B1); PG8_BAR; PG8_SCHED;
;             PG8_LDA(At, 0, 1); PG8_STAGE(PG8_SB(0, 0), b2, voffB); PG8_STAGE(PG8_SB(0, 1), b2 + hstep, voffB); PG8_STAGE(PG8_SA(0, 0), a2, voffA);
;             PG8_WAIT_V(8); PG8_WAIT_L(0); PG8_BAR; PG8_MMA(1, 0, At, B0); PG8_MMA(1, 1, At, B1); PG8_BAR; PG8_SCHED;
.LBB0_536:
	ds_read_b128 v[152:155], v149
	ds_read_b128 v[156:159], v149 offset:1024
	ds_read_b128 v[160:163], v149 offset:2048
	ds_read_b128 v[164:167], v149 offset:3072
	ds_read_b128 v[168:171], v150
	ds_read_b128 v[178:181], v150 offset:1024
	ds_read_b128 v[182:185], v150 offset:2048
	ds_read_b128 v[186:189], v150 offset:3072
	s_add_u32 s40, s38, 0xfff80080
	s_addc_u32 s41, s39, -1
	s_cmp_eq_u32 s86, 28
	s_cselect_b32 s43, s27, s41
	s_cselect_b32 s42, s76, s40
	s_cselect_b32 s41, s25, s85
	s_cselect_b32 s40, s77, s84
	v_lshl_add_u64 v[144:145], s[38:39], 0, v[136:137]
	s_add_i32 m0, s35, 0xc000
	ds_read_b128 v[190:193], v151
	ds_read_b128 v[194:197], v151 offset:1024
	ds_read_b128 v[198:201], v151 offset:2048
	ds_read_b128 v[202:205], v151 offset:3072
	ds_read_b128 v[206:209], v151 offset:4096
	ds_read_b128 v[210:213], v151 offset:5120
	ds_read_b128 v[214:217], v151 offset:6144
	ds_read_b128 v[218:221], v151 offset:7168
	global_load_lds_dwordx4 v[144:145], off
	v_lshl_add_u64 v[144:145], s[38:39], 0, v[138:139]
	s_add_i32 m0, s35, 0xe000
	s_nop 0
	global_load_lds_dwordx4 v[144:145], off
	s_waitcnt vmcnt(8)
	s_waitcnt lgkmcnt(0)
	s_setprio 1
	s_barrier
	s_waitcnt lgkmcnt(0)
	v_mfma_f32_16x16x32_bf16 v[124:127], v[152:155], v[190:193], v[124:127]
	v_mfma_f32_16x16x32_bf16 v[120:123], v[160:163], v[190:193], v[120:123]
	v_mfma_f32_16x16x32_bf16 v[116:119], v[152:155], v[198:201], v[116:119]
	v_mfma_f32_16x16x32_bf16 v[108:111], v[160:163], v[198:201], v[108:111]
	v_mfma_f32_16x16x32_bf16 v[100:103], v[152:155], v[206:209], v[100:103]
	v_mfma_f32_16x16x32_bf16 v[92:95], v[160:163], v[206:209], v[92:95]
	v_mfma_f32_16x16x32_bf16 v[84:87], v[152:155], v[214:217], v[84:87]
	v_mfma_f32_16x16x32_bf16 v[76:79], v[160:163], v[214:217], v[76:79]
	v_mfma_f32_16x16x32_bf16 v[124:127], v[156:159], v[194:197], v[124:127]
	v_mfma_f32_16x16x32_bf16 v[120:123], v[164:167], v[194:197], v[120:123]
	v_mfma_f32_16x16x32_bf16 v[116:119], v[156:159], v[202:205], v[116:119]
	v_mfma_f32_16x16x32_bf16 v[108:111], v[164:167], v[202:205], v[108:111]
	v_mfma_f32_16x16x32_bf16 v[100:103], v[156:159], v[210:213], v[100:103]
	v_mfma_f32_16x16x32_bf16 v[92:95], v[164:167], v[210:213], v[92:95]
	v_mfma_f32_16x16x32_bf16 v[84:87], v[156:159], v[218:221], v[84:87]
	v_mfma_f32_16x16x32_bf16 v[76:79], v[164:167], v[218:221], v[76:79]
	s_setprio 0
	s_setprio 1
	v_mfma_f32_16x16x32_bf16 v[112:115], v[168:171], v[190:193], v[112:115]
	v_mfma_f32_16x16x32_bf16 v[104:107], v[182:185], v[190:193], v[104:107]
	v_mfma_f32_16x16x32_bf16 v[96:99], v[168:171], v[198:201], v[96:99]
	v_mfma_f32_16x16x32_bf16 v[88:91], v[182:185], v[198:201], v[88:91]
	v_mfma_f32_16x16x32_bf16 v[80:83], v[168:171], v[206:209], v[80:83]
	v_mfma_f32_16x16x32_bf16 v[72:75], v[182:185], v[206:209], v[72:75]
	v_mfma_f32_16x16x32_bf16 v[68:71], v[168:171], v[214:217], v[68:71]
	v_mfma_f32_16x16x32_bf16 v[64:67], v[182:185], v[214:217], v[64:67]
	v_mfma_f32_16x16x32_bf16 v[112:115], v[178:181], v[194:197], v[112:115]
	v_mfma_f32_16x16x32_bf16 v[104:107], v[186:189], v[194:197], v[104:107]
	v_mfma_f32_16x16x32_bf16 v[96:99], v[178:181], v[202:205], v[96:99]
	v_mfma_f32_16x16x32_bf16 v[88:91], v[186:189], v[202:205], v[88:91]
	v_mfma_f32_16x16x32_bf16 v[80:83], v[178:181], v[210:213], v[80:83]
	v_mfma_f32_16x16x32_bf16 v[72:75], v[186:189], v[210:213], v[72:75]
	v_mfma_f32_16x16x32_bf16 v[68:71], v[178:181], v[218:221], v[68:71]
	v_mfma_f32_16x16x32_bf16 v[64:67], v[186:189], v[218:221], v[64:67]
	s_setprio 0
	s_barrier
	s_add_i32 s44, s62, s50
	v_lshl_add_u64 v[144:145], s[40:41], 0, v[130:131]
	s_mov_b32 m0, s44
	ds_read_b128 v[190:193], v151 offset:16384
	ds_read_b128 v[194:197], v151 offset:17408
	ds_read_b128 v[198:201], v151 offset:18432
	ds_read_b128 v[202:205], v151 offset:19456
	ds_read_b128 v[206:209], v151 offset:20480
	ds_read_b128 v[210:213], v151 offset:21504
	ds_read_b128 v[214:217], v151 offset:22528
	ds_read_b128 v[218:221], v151 offset:23552
	global_load_lds_dwordx4 v[144:145], off
	s_add_i32 m0, s44, 0x2000
	s_add_u32 s88, s40, 0x80000
	v_lshl_add_u64 v[172:173], s[40:41], 0, v[134:135]
	s_addc_u32 s89, s41, 0
	s_add_i32 s44, s63, s50
	global_load_lds_dwordx4 v[172:173], off
	v_lshl_add_u64 v[222:223], s[88:89], 0, v[130:131]
	s_mov_b32 m0, s44
	v_lshl_add_u64 v[224:225], s[42:43], 0, v[132:133]
	global_load_lds_dwordx4 v[222:223], off
	v_lshl_add_u64 v[222:223], s[88:89], 0, v[134:135]
	s_add_i32 m0, s44, 0x2000
	s_nop 0
	global_load_lds_dwordx4 v[222:223], off
	v_lshl_add_u64 v[222:223], s[42:43], 0, v[128:129]
	s_mov_b32 m0, s35
	s_nop 0
	global_load_lds_dwordx4 v[222:223], off
	s_mov_b32 m0, s52
	s_nop 0
	global_load_lds_dwordx4 v[224:225], off
	s_waitcnt vmcnt(8)
	s_waitcnt lgkmcnt(0)
	s_setprio 1
	s_barrier
; #define PG8_STAGE(bufoff, gbase, voff) do { _Pragma("unroll") for (int _i = 0; _i < 2; ++_i) \
;         __builtin_amdgcn_global_load_lds((const unsigned*)((const char*)(gbase) + (voff)[_i]), (PG8_LAS unsigned*)(lds + (bufoff) + ldsw + _i * 8192), 16, 0, 0); } while (0)
; #define PG8_LDA(dst, b, h) do { _Pragma("unroll") for (int m = 0; m < 4; ++m) _Pragma("unroll") for (int k = 0; k < 2; ++k) dst[m][k] = *(const PG8_LAS bf16x8*)(lds + PG8_SA(b, h) + aoff + m * 2048 + k * 1024); } while (0)
; #define PG8_LDB(dst, b, h) do { _Pragma("unroll") for (int n = 0; n < 2; ++n) _Pragma("unroll") for (int k = 0; k < 2; ++k) dst[n][k] = *(const PG8_LAS bf16x8*)(lds + PG8_SB(b, h) + boff + n * 2048 + k * 1024); } while (0)
; #define PG8_MMA(ai, bj, At, Bt) do { __builtin_amdgcn_s_setprio(1); _Pragma("unroll") for (int m = 0; m < 4; ++m) _Pragma("unroll") for (int n = 0; n < 2; ++n) _Pragma("unroll") for (int k = 0; k < 2; ++k) \
;         acc[ai][bj][m][n] = __builtin_amdgcn_mfma_f32_16x16x32_bf16(Bt[n][k], At[m][k], acc[ai][bj][m][n], 0, 0, 0); __builtin_amdgcn_s_setprio(0); } while (0)
; #define PG8_WAIT_V(n) asm volatile("s_waitcnt vmcnt(" #n ")" ::: "memory")
; #define PG8_WAIT_L(n) asm volatile("s_waitcnt lgkmcnt(" #n ")" ::: "memory")
; #define PG8_BAR __builtin_amdgcn_s_barrier()
; #define PG8_SCHED __builtin_amdgcn_sched_barrier(0)
; template <class Epi, class Sched, bool ALIGN_EPI = false, bool SP2 = false>
; __device__ __forceinline__ void gemm_phase(PG8_LAS unsigned char* lds, const Gemm g, const Sched& S, const Epi& E) {
;     ...
;             PG8_WAIT_V(8); PG8_WAIT_L(0); PG8_BAR; PG8_MMA(1, 0, At, B0); PG8_MMA(1, 1, At, B1); PG8_BAR; PG8_SCHED;
;             PG8_LDB(B0, 1, 0); PG8_LDB(B1, 1, 1); PG8_SCHED; PG8_LDA(At, 1, 0); PG8_STAGE(PG8_SA(0, 1), a2 + hstep, voffA);
;             PG8_WAIT_V(8); PG8_WAIT_L(0); PG8_BAR; PG8_MMA(0, 0, At, B0); PG8_MMA(0, 1, At, B1); PG8_BAR; PG8_SCHED;
	s_waitcnt lgkmcnt(0)
	v_mfma_f32_16x16x32_bf16 v[60:63], v[152:155], v[190:193], v[60:63]
	v_mfma_f32_16x16x32_bf16 v[56:59], v[160:163], v[190:193], v[56:59]
	v_mfma_f32_16x16x32_bf16 v[52:55], v[152:155], v[198:201], v[52:55]
	v_mfma_f32_16x16x32_bf16 v[44:47], v[160:163], v[198:201], v[44:47]
	v_mfma_f32_16x16x32_bf16 v[36:39], v[152:155], v[206:209], v[36:39]
	v_mfma_f32_16x16x32_bf16 v[28:31], v[160:163], v[206:209], v[28:31]
	v_mfma_f32_16x16x32_bf16 v[20:23], v[152:155], v[214:217], v[20:23]
	v_mfma_f32_16x16x32_bf16 v[12:15], v[160:163], v[214:217], v[12:15]
	v_mfma_f32_16x16x32_bf16 v[60:63], v[156:159], v[194:197], v[60:63]
	v_mfma_f32_16x16x32_bf16 v[56:59], v[164:167], v[194:197], v[56:59]
	v_mfma_f32_16x16x32_bf16 v[52:55], v[156:159], v[202:205], v[52:55]
	v_mfma_f32_16x16x32_bf16 v[44:47], v[164:167], v[202:205], v[44:47]
	v_mfma_f32_16x16x32_bf16 v[36:39], v[156:159], v[210:213], v[36:39]
	v_mfma_f32_16x16x32_bf16 v[28:31], v[164:167], v[210:213], v[28:31]
	v_mfma_f32_16x16x32_bf16 v[20:23], v[156:159], v[218:221], v[20:23]
	v_mfma_f32_16x16x32_bf16 v[12:15], v[164:167], v[218:221], v[12:15]
	s_setprio 0
	s_setprio 1
	v_mfma_f32_16x16x32_bf16 v[48:51], v[168:171], v[190:193], v[48:51]
	v_mfma_f32_16x16x32_bf16 v[40:43], v[182:185], v[190:193], v[40:43]
	v_mfma_f32_16x16x32_bf16 v[32:35], v[168:171], v[198:201], v[32:35]
	v_mfma_f32_16x16x32_bf16 v[24:27], v[182:185], v[198:201], v[24:27]
	v_mfma_f32_16x16x32_bf16 v[16:19], v[168:171], v[206:209], v[16:19]
	v_mfma_f32_16x16x32_bf16 v[8:11], v[182:185], v[206:209], v[8:11]
	v_mfma_f32_16x16x32_bf16 v[4:7], v[168:171], v[214:217], v[4:7]
	v_mfma_f32_16x16x32_bf16 v[0:3], v[182:185], v[214:217], v[0:3]
	v_mfma_f32_16x16x32_bf16 v[48:51], v[178:181], v[194:197], v[48:51]
	v_mfma_f32_16x16x32_bf16 v[40:43], v[186:189], v[194:197], v[40:43]
	v_mfma_f32_16x16x32_bf16 v[32:35], v[178:181], v[202:205], v[32:35]
	v_mfma_f32_16x16x32_bf16 v[24:27], v[186:189], v[202:205], v[24:27]
	v_mfma_f32_16x16x32_bf16 v[16:19], v[178:181], v[210:213], v[16:19]
	v_mfma_f32_16x16x32_bf16 v[8:11], v[186:189], v[210:213], v[8:11]
	v_mfma_f32_16x16x32_bf16 v[4:7], v[178:181], v[218:221], v[4:7]
	v_mfma_f32_16x16x32_bf16 v[0:3], v[186:189], v[218:221], v[0:3]
	s_setprio 0
	s_barrier
	s_add_i32 s44, 0, 0x18000
	s_add_i32 s45, 0, 0x1c000
	v_add_u32_e32 v164, s44, v147
	v_add_u32_e32 v177, s45, v147
	ds_read_b128 v[152:155], v164
	ds_read_b128 v[156:159], v164 offset:1024
	ds_read_b128 v[160:163], v164 offset:2048
	ds_read_b128 v[164:167], v164 offset:3072
	ds_read_b128 v[168:171], v177
	ds_read_b128 v[178:181], v177 offset:1024
	ds_read_b128 v[182:185], v177 offset:2048
	ds_read_b128 v[186:189], v177 offset:3072
	s_add_u32 s42, s42, 0x80000
	s_addc_u32 s43, s43, 0
	s_mov_b32 m0, s53
	v_lshl_add_u64 v[226:227], s[42:43], 0, v[128:129]
	ds_read_b128 v[190:193], v151 offset:32768
	ds_read_b128 v[194:197], v151 offset:33792
	ds_read_b128 v[198:201], v151 offset:34816
	ds_read_b128 v[202:205], v151 offset:35840
	ds_read_b128 v[206:209], v151 offset:36864
	ds_read_b128 v[210:213], v151 offset:37888
	ds_read_b128 v[214:217], v151 offset:38912
	ds_read_b128 v[218:221], v151 offset:39936
	global_load_lds_dwordx4 v[226:227], off
	v_lshl_add_u64 v[226:227], s[42:43], 0, v[132:133]
	s_mov_b32 m0, s56
	s_nop 0
	global_load_lds_dwordx4 v[226:227], off
	s_waitcnt vmcnt(8)
	s_waitcnt lgkmcnt(0)
	s_setprio 1
	s_barrier
	s_waitcnt lgkmcnt(0)
	v_mfma_f32_16x16x32_bf16 v[124:127], v[152:155], v[190:193], v[124:127]
	v_mfma_f32_16x16x32_bf16 v[120:123], v[160:163], v[190:193], v[120:123]
	v_mfma_f32_16x16x32_bf16 v[116:119], v[152:155], v[198:201], v[116:119]
	v_mfma_f32_16x16x32_bf16 v[108:111], v[160:163], v[198:201], v[108:111]
	v_mfma_f32_16x16x32_bf16 v[100:103], v[152:155], v[206:209], v[100:103]
	v_mfma_f32_16x16x32_bf16 v[92:95], v[160:163], v[206:209], v[92:95]
	v_mfma_f32_16x16x32_bf16 v[84:87], v[152:155], v[214:217], v[84:87]
	v_mfma_f32_16x16x32_bf16 v[76:79], v[160:163], v[214:217], v[76:79]
	v_mfma_f32_16x16x32_bf16 v[124:127], v[156:159], v[194:197], v[124:127]
	v_mfma_f32_16x16x32_bf16 v[120:123], v[164:167], v[194:197], v[120:123]
	v_mfma_f32_16x16x32_bf16 v[116:119], v[156:159], v[202:205], v[116:119]
	v_mfma_f32_16x16x32_bf16 v[108:111], v[164:167], v[202:205], v[108:111]
	v_mfma_f32_16x16x32_bf16 v[100:103], v[156:159], v[210:213], v[100:103]
	v_mfma_f32_16x16x32_bf16 v[92:95], v[164:167], v[210:213], v[92:95]
	v_mfma_f32_16x16x32_bf16 v[84:87], v[156:159], v[218:221], v[84:87]
	v_mfma_f32_16x16x32_bf16 v[76:79], v[164:167], v[218:221], v[76:79]
	s_setprio 0
	s_setprio 1
	v_mfma_f32_16x16x32_bf16 v[112:115], v[168:171], v[190:193], v[112:115]
	v_mfma_f32_16x16x32_bf16 v[104:107], v[182:185], v[190:193], v[104:107]
	v_mfma_f32_16x16x32_bf16 v[96:99], v[168:171], v[198:201], v[96:99]
	v_mfma_f32_16x16x32_bf16 v[88:91], v[182:185], v[198:201], v[88:91]
	v_mfma_f32_16x16x32_bf16 v[80:83], v[168:171], v[206:209], v[80:83]
	v_mfma_f32_16x16x32_bf16 v[72:75], v[182:185], v[206:209], v[72:75]
	v_mfma_f32_16x16x32_bf16 v[68:71], v[168:171], v[214:217], v[68:71]
	v_mfma_f32_16x16x32_bf16 v[64:67], v[182:185], v[214:217], v[64:67]
	v_mfma_f32_16x16x32_bf16 v[112:115], v[178:181], v[194:197], v[112:115]
	v_mfma_f32_16x16x32_bf16 v[104:107], v[186:189], v[194:197], v[104:107]
	v_mfma_f32_16x16x32_bf16 v[96:99], v[178:181], v[202:205], v[96:99]
	v_mfma_f32_16x16x32_bf16 v[88:91], v[186:189], v[202:205], v[88:91]
	v_mfma_f32_16x16x32_bf16 v[80:83], v[178:181], v[210:213], v[80:83]
	v_mfma_f32_16x16x32_bf16 v[72:75], v[186:189], v[210:213], v[72:75]
	v_mfma_f32_16x16x32_bf16 v[68:71], v[178:181], v[218:221], v[68:71]
	v_mfma_f32_16x16x32_bf16 v[64:67], v[186:189], v[218:221], v[64:67]
	s_setprio 0
	s_barrier
; #define PG8_STAGE(bufoff, gbase, voff) do { _Pragma("unroll") for (int _i = 0; _i < 2; ++_i) \
;         __builtin_amdgcn_global_load_lds((const unsigned*)((const char*)(gbase) + (voff)[_i]), (PG8_LAS unsigned*)(lds + (bufoff) + ldsw + _i * 8192), 16, 0, 0); } while (0)
; #define PG8_LDA(dst, b, h) do { _Pragma("unroll") for (int m = 0; m < 4; ++m) _Pragma("unroll") for (int k = 0; k < 2; ++k) dst[m][k] = *(const PG8_LAS bf16x8*)(lds + PG8_SA(b, h) + aoff + m * 2048 + k * 1024); } while (0)
; #define PG8_MMA(ai, bj, At, Bt) do { __builtin_amdgcn_s_setprio(1); _Pragma("unroll") for (int m = 0; m < 4; ++m) _Pragma("unroll") for (int n = 0; n < 2; ++n) _Pragma("unroll") for (int k = 0; k < 2; ++k) \
;         acc[ai][bj][m][n] = __builtin_amdgcn_mfma_f32_16x16x32_bf16(Bt[n][k], At[m][k], acc[ai][bj][m][n], 0, 0, 0); __builtin_amdgcn_s_setprio(0); } while (0)
; #define PG8_WAIT_V(n) asm volatile("s_waitcnt vmcnt(" #n ")" ::: "memory")
; #define PG8_WAIT_L(n) asm volatile("s_waitcnt lgkmcnt(" #n ")" ::: "memory")
; #define PG8_BAR __builtin_amdgcn_s_barrier()
; #define PG8_SCHED __builtin_amdgcn_sched_barrier(0)
; template <class Epi, class Sched, bool ALIGN_EPI = false, bool SP2 = false>
; __device__ __forceinline__ void gemm_phase(PG8_LAS unsigned char* lds, const Gemm g, const Sched& S, const Epi& E) {
;     ...
;         for (int t = 0; t < nt; t += 2) {
;             const bool last = (t == nt - 2);
;             const char* a1 = cA + (size_t)(t + 1) * kstep;
;             const char* a2 = last ? nA : cA + (size_t)(t + 2) * kstep; const char* b2 = last ? nB : cB + (size_t)(t + 2) * kstep;
;     ...
;             PG8_LDA(At, 1, 1); PG8_STAGE(PG8_SB(1, 0), b3, voffB); PG8_STAGE(PG8_SB(1, 1), b3 + hstep, voffB); PG8_STAGE(PG8_SA(1, 0), a3, voffA);
;             PG8_WAIT_V(8); PG8_WAIT_L(0); PG8_BAR; PG8_MMA(1, 0, At, B0); PG8_MMA(1, 1, At, B1); PG8_BAR; PG8_SCHED;
	s_add_i32 s42, s44, s50
	v_lshl_add_u64 v[144:145], v[144:145], 0, s[14:15]
	s_mov_b32 m0, s42
	ds_read_b128 v[190:193], v151 offset:49152
	ds_read_b128 v[194:197], v151 offset:50176
	ds_read_b128 v[198:201], v151 offset:51200
	ds_read_b128 v[202:205], v151 offset:52224
	ds_read_b128 v[206:209], v151 offset:53248
	ds_read_b128 v[210:213], v151 offset:54272
	ds_read_b128 v[214:217], v151 offset:55296
	ds_read_b128 v[218:221], v151 offset:56320
	global_load_lds_dwordx4 v[144:145], off
	s_add_i32 m0, s42, 0x2000
	s_add_u32 s40, s40, 0x80080
	v_lshl_add_u64 v[144:145], v[172:173], 0, s[14:15]
	s_addc_u32 s41, s41, 0
	s_add_i32 s42, s45, s50
	global_load_lds_dwordx4 v[144:145], off
	v_lshl_add_u64 v[144:145], s[40:41], 0, v[130:131]
	s_mov_b32 m0, s42
	s_nop 0
	global_load_lds_dwordx4 v[144:145], off
	v_lshl_add_u64 v[144:145], s[40:41], 0, v[134:135]
	s_add_i32 m0, s42, 0x2000
	s_nop 0
	global_load_lds_dwordx4 v[144:145], off
	v_lshl_add_u64 v[144:145], v[222:223], 0, s[14:15]
	s_mov_b32 m0, s60
	s_nop 0
	global_load_lds_dwordx4 v[144:145], off
	v_lshl_add_u64 v[144:145], v[224:225], 0, s[14:15]
	s_mov_b32 m0, s61
	s_nop 0
	global_load_lds_dwordx4 v[144:145], off
	s_waitcnt vmcnt(8)
	s_waitcnt lgkmcnt(0)
	s_setprio 1
	s_barrier
	s_waitcnt lgkmcnt(0)
	v_mfma_f32_16x16x32_bf16 v[60:63], v[152:155], v[190:193], v[60:63]
	v_mfma_f32_16x16x32_bf16 v[56:59], v[160:163], v[190:193], v[56:59]
	v_mfma_f32_16x16x32_bf16 v[52:55], v[152:155], v[198:201], v[52:55]
	v_mfma_f32_16x16x32_bf16 v[44:47], v[160:163], v[198:201], v[44:47]
	v_mfma_f32_16x16x32_bf16 v[36:39], v[152:155], v[206:209], v[36:39]
	v_mfma_f32_16x16x32_bf16 v[28:31], v[160:163], v[206:209], v[28:31]
	v_mfma_f32_16x16x32_bf16 v[20:23], v[152:155], v[214:217], v[20:23]
	v_mfma_f32_16x16x32_bf16 v[12:15], v[160:163], v[214:217], v[12:15]
	v_mfma_f32_16x16x32_bf16 v[60:63], v[156:159], v[194:197], v[60:63]
	v_mfma_f32_16x16x32_bf16 v[56:59], v[164:167], v[194:197], v[56:59]
	v_mfma_f32_16x16x32_bf16 v[52:55], v[156:159], v[202:205], v[52:55]
	v_mfma_f32_16x16x32_bf16 v[44:47], v[164:167], v[202:205], v[44:47]
	v_mfma_f32_16x16x32_bf16 v[36:39], v[156:159], v[210:213], v[36:39]
	v_mfma_f32_16x16x32_bf16 v[28:31], v[164:167], v[210:213], v[28:31]
	v_mfma_f32_16x16x32_bf16 v[20:23], v[156:159], v[218:221], v[20:23]
	v_mfma_f32_16x16x32_bf16 v[12:15], v[164:167], v[218:221], v[12:15]
	s_setprio 0
	s_setprio 1
	v_mfma_f32_16x16x32_bf16 v[48:51], v[168:171], v[190:193], v[48:51]
	v_mfma_f32_16x16x32_bf16 v[40:43], v[182:185], v[190:193], v[40:43]
	v_mfma_f32_16x16x32_bf16 v[32:35], v[168:171], v[198:201], v[32:35]
	v_mfma_f32_16x16x32_bf16 v[24:27], v[182:185], v[198:201], v[24:27]
	v_mfma_f32_16x16x32_bf16 v[16:19], v[168:171], v[206:209], v[16:19]
	v_mfma_f32_16x16x32_bf16 v[8:11], v[182:185], v[206:209], v[8:11]
	v_mfma_f32_16x16x32_bf16 v[4:7], v[168:171], v[214:217], v[4:7]
	v_mfma_f32_16x16x32_bf16 v[0:3], v[182:185], v[214:217], v[0:3]
	v_mfma_f32_16x16x32_bf16 v[48:51], v[178:181], v[194:197], v[48:51]
	v_mfma_f32_16x16x32_bf16 v[40:43], v[186:189], v[194:197], v[40:43]
	v_mfma_f32_16x16x32_bf16 v[32:35], v[178:181], v[202:205], v[32:35]
	v_mfma_f32_16x16x32_bf16 v[24:27], v[186:189], v[202:205], v[24:27]
	v_mfma_f32_16x16x32_bf16 v[16:19], v[178:181], v[210:213], v[16:19]
	v_mfma_f32_16x16x32_bf16 v[8:11], v[186:189], v[210:213], v[8:11]
	v_mfma_f32_16x16x32_bf16 v[4:7], v[178:181], v[218:221], v[4:7]
	v_mfma_f32_16x16x32_bf16 v[0:3], v[186:189], v[218:221], v[0:3]
	s_setprio 0
	s_barrier
	s_add_i32 s86, s86, 2
	s_add_u32 s38, s38, 0x100
	s_addc_u32 s39, s39, 0
	s_add_u32 s84, s84, 0x100
	s_addc_u32 s85, s85, 0
	s_cmp_gt_u32 s86, 29
	s_cbranch_scc0 .LBB0_536
	s_and_b64 vcc, exec, s[16:17]
	s_cbranch_vccz .LBB0_539
	s_barrier

; #define PG8_STAGE(bufoff, gbase, voff) do { _Pragma("unroll") for (int _i = 0; _i < 2; ++_i) \
;         __builtin_amdgcn_global_load_lds((const unsigned*)((const char*)(gbase) + (voff)[_i]), (PG8_LAS unsigned*)(lds + (bufoff) + ldsw + _i * 8192), 16, 0, 0); } while (0)
; #define PG8_LDA(dst, b, h) do { _Pragma("unroll") for (int m = 0; m < 4; ++m) _Pragma("unroll") for (int k = 0; k < 2; ++k) dst[m][k] = *(const PG8_LAS bf16x8*)(lds + PG8_SA(b, h) + aoff + m * 2048 + k * 1024); } while (0)
; #define PG8_LDB(dst, b, h) do { _Pragma("unroll") for (int n = 0; n < 2; ++n) _Pragma("unroll") for (int k = 0; k < 2; ++k) dst[n][k] = *(const PG8_LAS bf16x8*)(lds + PG8_SB(b, h) + boff + n * 2048 + k * 1024); } while (0)
; #define PG8_MMA(ai, bj, At, Bt) do { __builtin_amdgcn_s_setprio(1); _Pragma("unroll") for (int m = 0; m < 4; ++m) _Pragma("unroll") for (int n = 0; n < 2; ++n) _Pragma("unroll") for (int k = 0; k < 2; ++k) \
;         acc[ai][bj][m][n] = __builtin_amdgcn_mfma_f32_16x16x32_bf16(Bt[n][k], At[m][k], acc[ai][bj][m][n], 0, 0, 0); __builtin_amdgcn_s_setprio(0); } while (0)
; #define PG8_WAIT_V(n) asm volatile("s_waitcnt vmcnt(" #n ")" ::: "memory")
; #define PG8_BAR __builtin_amdgcn_s_barrier()
; template <class Epi, class Sched, bool ALIGN_EPI = false, bool SP2 = false>
; __device__ __forceinline__ void gemm_phase(PG8_LAS unsigned char* lds, const Gemm g, const Sched& S, const Epi& E) {
;     ...
;         for (int t = 0; t < nt; t += 2) {
;             const bool last = (t == nt - 2);
;             const char* a1 = cA + (size_t)(t + 1) * kstep;
;             const char* a2 = last ? nA : cA + (size_t)(t + 2) * kstep; const char* b2 = last ? nB : cB + (size_t)(t + 2) * kstep;
;             const char* a3 = a2 + kstep; const char* b3 = b2 + kstep;
;             if (last && has_next) S.a_ready(nxt);
;             if constexpr (SP2) {
;             PG8_LDB(B0, 0, 0); PG8_LDB(B1, 0, 1); PG8_SCHED; PG8_LDA(At, 0, 0); PG8_STAGE(PG8_SA(1, 1), a1 + hstep, voffA);
;             PG8_WAIT_V(8); PG8_WAIT_L(0); PG8_BAR; PG8_MMA(0, 0, At, B0); PG8_MMA(0, 1, At, B1); PG8_BAR; PG8_SCHED;
;             PG8_LDA(At, 0, 1); PG8_STAGE(PG8_SB(0, 0), b2, voffB); PG8_STAGE(PG8_SB(0, 1), b2 + hstep, voffB); PG8_STAGE(PG8_SA(0, 0), a2, voffA);
;             PG8_WAIT_V(8); PG8_WAIT_L(0); PG8_BAR; PG8_MMA(1, 0, At, B0); PG8_MMA(1, 1, At, B1); PG8_BAR; PG8_SCHED;
.LBB0_671:
	ds_read_b128 v[120:123], v180
	ds_read_b128 v[124:127], v180 offset:1024
	ds_read_b128 v[128:131], v180 offset:2048
	ds_read_b128 v[132:135], v180 offset:3072
	ds_read_b128 v[136:139], v181
	ds_read_b128 v[140:143], v181 offset:1024
	ds_read_b128 v[170:173], v181 offset:2048
	ds_read_b128 v[184:187], v181 offset:3072
	s_add_u32 s44, s56, 0xfff80080
	s_addc_u32 s45, s57, -1
	s_cmp_eq_u32 vcc_hi, 28
	s_cselect_b32 s61, s47, s45
	s_cselect_b32 s60, s95, s44
	s_cselect_b32 s59, s43, vcc_lo
	s_cselect_b32 s58, s96, s97
	v_lshl_add_u64 v[220:221], s[56:57], 0, v[162:163]
	s_add_i32 m0, s72, 0xc000
	ds_read_b128 v[188:191], v182
	ds_read_b128 v[192:195], v182 offset:1024
	ds_read_b128 v[196:199], v182 offset:2048
	ds_read_b128 v[200:203], v182 offset:3072
	ds_read_b128 v[204:207], v182 offset:4096
	ds_read_b128 v[208:211], v182 offset:5120
	ds_read_b128 v[212:215], v182 offset:6144
	ds_read_b128 v[216:219], v182 offset:7168
	global_load_lds_dwordx4 v[220:221], off
	v_lshl_add_u64 v[220:221], s[56:57], 0, v[164:165]
	s_add_i32 m0, s72, 0xe000
	s_nop 0
	global_load_lds_dwordx4 v[220:221], off
	s_waitcnt vmcnt(8)
	s_waitcnt lgkmcnt(0)
	s_setprio 1
	s_barrier
	s_waitcnt lgkmcnt(0)
	v_mfma_f32_16x16x32_bf16 v[144:147], v[120:123], v[188:191], v[144:147]
	v_mfma_f32_16x16x32_bf16 v[60:63], v[128:131], v[188:191], v[60:63]
	v_mfma_f32_16x16x32_bf16 v[116:119], v[120:123], v[196:199], v[116:119]
	v_mfma_f32_16x16x32_bf16 v[52:55], v[128:131], v[196:199], v[52:55]
	v_mfma_f32_16x16x32_bf16 v[108:111], v[120:123], v[204:207], v[108:111]
	v_mfma_f32_16x16x32_bf16 v[44:47], v[128:131], v[204:207], v[44:47]
	v_mfma_f32_16x16x32_bf16 v[96:99], v[120:123], v[212:215], v[96:99]
	v_mfma_f32_16x16x32_bf16 v[36:39], v[128:131], v[212:215], v[36:39]
	v_mfma_f32_16x16x32_bf16 v[144:147], v[124:127], v[192:195], v[144:147]
	v_mfma_f32_16x16x32_bf16 v[60:63], v[132:135], v[192:195], v[60:63]
	v_mfma_f32_16x16x32_bf16 v[116:119], v[124:127], v[200:203], v[116:119]
	v_mfma_f32_16x16x32_bf16 v[52:55], v[132:135], v[200:203], v[52:55]
	v_mfma_f32_16x16x32_bf16 v[108:111], v[124:127], v[208:211], v[108:111]
	v_mfma_f32_16x16x32_bf16 v[44:47], v[132:135], v[208:211], v[44:47]
	v_mfma_f32_16x16x32_bf16 v[96:99], v[124:127], v[216:219], v[96:99]
	v_mfma_f32_16x16x32_bf16 v[36:39], v[132:135], v[216:219], v[36:39]
	s_setprio 0
	s_setprio 1
	v_mfma_f32_16x16x32_bf16 v[148:151], v[136:139], v[188:191], v[148:151]
	v_mfma_f32_16x16x32_bf16 v[56:59], v[170:173], v[188:191], v[56:59]
	v_mfma_f32_16x16x32_bf16 v[112:115], v[136:139], v[196:199], v[112:115]
	v_mfma_f32_16x16x32_bf16 v[48:51], v[170:173], v[196:199], v[48:51]
	v_mfma_f32_16x16x32_bf16 v[104:107], v[136:139], v[204:207], v[104:107]
	v_mfma_f32_16x16x32_bf16 v[40:43], v[170:173], v[204:207], v[40:43]
	v_mfma_f32_16x16x32_bf16 v[100:103], v[136:139], v[212:215], v[100:103]
	v_mfma_f32_16x16x32_bf16 v[32:35], v[170:173], v[212:215], v[32:35]
	v_mfma_f32_16x16x32_bf16 v[148:151], v[140:143], v[192:195], v[148:151]
	v_mfma_f32_16x16x32_bf16 v[56:59], v[184:187], v[192:195], v[56:59]
	v_mfma_f32_16x16x32_bf16 v[112:115], v[140:143], v[200:203], v[112:115]
	v_mfma_f32_16x16x32_bf16 v[48:51], v[184:187], v[200:203], v[48:51]
	v_mfma_f32_16x16x32_bf16 v[104:107], v[140:143], v[208:211], v[104:107]
	v_mfma_f32_16x16x32_bf16 v[40:43], v[184:187], v[208:211], v[40:43]
	v_mfma_f32_16x16x32_bf16 v[100:103], v[140:143], v[216:219], v[100:103]
	v_mfma_f32_16x16x32_bf16 v[32:35], v[184:187], v[216:219], v[32:35]
	s_setprio 0
	s_barrier
	s_add_i32 s44, s89, s67
	v_lshl_add_u64 v[220:221], s[58:59], 0, v[154:155]
	s_mov_b32 m0, s44
	ds_read_b128 v[188:191], v182 offset:16384
	ds_read_b128 v[192:195], v182 offset:17408
	ds_read_b128 v[196:199], v182 offset:18432
	ds_read_b128 v[200:203], v182 offset:19456
	ds_read_b128 v[204:207], v182 offset:20480
	ds_read_b128 v[208:211], v182 offset:21504
	ds_read_b128 v[212:215], v182 offset:22528
	ds_read_b128 v[216:219], v182 offset:23552
	global_load_lds_dwordx4 v[220:221], off
	s_add_i32 m0, s44, 0x2000
	s_add_u32 s44, s58, 0x80000
	v_lshl_add_u64 v[222:223], s[58:59], 0, v[158:159]
	s_addc_u32 s45, s59, 0
	s_add_i32 s54, s90, s67
	global_load_lds_dwordx4 v[222:223], off
	v_lshl_add_u64 v[224:225], s[44:45], 0, v[154:155]
	s_mov_b32 m0, s54
	v_lshl_add_u64 v[226:227], s[60:61], 0, v[156:157]
	global_load_lds_dwordx4 v[224:225], off
	v_lshl_add_u64 v[224:225], s[44:45], 0, v[158:159]
	s_add_i32 m0, s54, 0x2000
	s_nop 0
	global_load_lds_dwordx4 v[224:225], off
	v_lshl_add_u64 v[224:225], s[60:61], 0, v[152:153]
	s_mov_b32 m0, s72
	s_nop 0
	global_load_lds_dwordx4 v[224:225], off
	s_mov_b32 m0, s73
	s_nop 0
	global_load_lds_dwordx4 v[226:227], off
	s_waitcnt vmcnt(8)
	s_waitcnt lgkmcnt(0)
	s_setprio 1
	s_barrier
; #define PG8_STAGE(bufoff, gbase, voff) do { _Pragma("unroll") for (int _i = 0; _i < 2; ++_i) \
;         __builtin_amdgcn_global_load_lds((const unsigned*)((const char*)(gbase) + (voff)[_i]), (PG8_LAS unsigned*)(lds + (bufoff) + ldsw + _i * 8192), 16, 0, 0); } while (0)
; #define PG8_LDA(dst, b, h) do { _Pragma("unroll") for (int m = 0; m < 4; ++m) _Pragma("unroll") for (int k = 0; k < 2; ++k) dst[m][k] = *(const PG8_LAS bf16x8*)(lds + PG8_SA(b, h) + aoff + m * 2048 + k * 1024); } while (0)
; #define PG8_LDB(dst, b, h) do { _Pragma("unroll") for (int n = 0; n < 2; ++n) _Pragma("unroll") for (int k = 0; k < 2; ++k) dst[n][k] = *(const PG8_LAS bf16x8*)(lds + PG8_SB(b, h) + boff + n * 2048 + k * 1024); } while (0)
; #define PG8_MMA(ai, bj, At, Bt) do { __builtin_amdgcn_s_setprio(1); _Pragma("unroll") for (int m = 0; m < 4; ++m) _Pragma("unroll") for (int n = 0; n < 2; ++n) _Pragma("unroll") for (int k = 0; k < 2; ++k) \
;         acc[ai][bj][m][n] = __builtin_amdgcn_mfma_f32_16x16x32_bf16(Bt[n][k], At[m][k], acc[ai][bj][m][n], 0, 0, 0); __builtin_amdgcn_s_setprio(0); } while (0)
; #define PG8_WAIT_V(n) asm volatile("s_waitcnt vmcnt(" #n ")" ::: "memory")
; #define PG8_WAIT_L(n) asm volatile("s_waitcnt lgkmcnt(" #n ")" ::: "memory")
; #define PG8_BAR __builtin_amdgcn_s_barrier()
; #define PG8_SCHED __builtin_amdgcn_sched_barrier(0)
; template <class Epi, class Sched, bool ALIGN_EPI = false, bool SP2 = false>
; __device__ __forceinline__ void gemm_phase(PG8_LAS unsigned char* lds, const Gemm g, const Sched& S, const Epi& E) {
;     ...
;             PG8_WAIT_V(8); PG8_WAIT_L(0); PG8_BAR; PG8_MMA(1, 0, At, B0); PG8_MMA(1, 1, At, B1); PG8_BAR; PG8_SCHED;
;             PG8_LDB(B0, 1, 0); PG8_LDB(B1, 1, 1); PG8_SCHED; PG8_LDA(At, 1, 0); PG8_STAGE(PG8_SA(0, 1), a2 + hstep, voffA);
;             PG8_WAIT_V(8); PG8_WAIT_L(0); PG8_BAR; PG8_MMA(0, 0, At, B0); PG8_MMA(0, 1, At, B1); PG8_BAR; PG8_SCHED;
	s_waitcnt lgkmcnt(0)
	v_mfma_f32_16x16x32_bf16 v[92:95], v[120:123], v[188:191], v[92:95]
	v_mfma_f32_16x16x32_bf16 v[28:31], v[128:131], v[188:191], v[28:31]
	v_mfma_f32_16x16x32_bf16 v[84:87], v[120:123], v[196:199], v[84:87]
	v_mfma_f32_16x16x32_bf16 v[8:11], v[128:131], v[196:199], v[8:11]
	v_mfma_f32_16x16x32_bf16 v[76:79], v[120:123], v[204:207], v[76:79]
	v_mfma_f32_16x16x32_bf16 v[20:23], v[128:131], v[204:207], v[20:23]
	v_mfma_f32_16x16x32_bf16 v[68:71], v[120:123], v[212:215], v[68:71]
	v_mfma_f32_16x16x32_bf16 v[16:19], v[128:131], v[212:215], v[16:19]
	v_mfma_f32_16x16x32_bf16 v[92:95], v[124:127], v[192:195], v[92:95]
	v_mfma_f32_16x16x32_bf16 v[28:31], v[132:135], v[192:195], v[28:31]
	v_mfma_f32_16x16x32_bf16 v[84:87], v[124:127], v[200:203], v[84:87]
	v_mfma_f32_16x16x32_bf16 v[8:11], v[132:135], v[200:203], v[8:11]
	v_mfma_f32_16x16x32_bf16 v[76:79], v[124:127], v[208:211], v[76:79]
	v_mfma_f32_16x16x32_bf16 v[20:23], v[132:135], v[208:211], v[20:23]
	v_mfma_f32_16x16x32_bf16 v[68:71], v[124:127], v[216:219], v[68:71]
	v_mfma_f32_16x16x32_bf16 v[16:19], v[132:135], v[216:219], v[16:19]
	s_setprio 0
	s_setprio 1
	v_mfma_f32_16x16x32_bf16 v[88:91], v[136:139], v[188:191], v[88:91]
	v_mfma_f32_16x16x32_bf16 v[24:27], v[170:173], v[188:191], v[24:27]
	v_mfma_f32_16x16x32_bf16 v[80:83], v[136:139], v[196:199], v[80:83]
	v_mfma_f32_16x16x32_bf16 v[0:3], v[170:173], v[196:199], v[0:3]
	v_mfma_f32_16x16x32_bf16 v[72:75], v[136:139], v[204:207], v[72:75]
	v_mfma_f32_16x16x32_bf16 v[4:7], v[170:173], v[204:207], v[4:7]
	v_mfma_f32_16x16x32_bf16 v[64:67], v[136:139], v[212:215], v[64:67]
	v_mfma_f32_16x16x32_bf16 v[12:15], v[170:173], v[212:215], v[12:15]
	v_mfma_f32_16x16x32_bf16 v[88:91], v[140:143], v[192:195], v[88:91]
	v_mfma_f32_16x16x32_bf16 v[24:27], v[184:187], v[192:195], v[24:27]
	v_mfma_f32_16x16x32_bf16 v[80:83], v[140:143], v[200:203], v[80:83]
	v_mfma_f32_16x16x32_bf16 v[0:3], v[184:187], v[200:203], v[0:3]
	v_mfma_f32_16x16x32_bf16 v[72:75], v[140:143], v[208:211], v[72:75]
	v_mfma_f32_16x16x32_bf16 v[4:7], v[184:187], v[208:211], v[4:7]
	v_mfma_f32_16x16x32_bf16 v[64:67], v[140:143], v[216:219], v[64:67]
	v_mfma_f32_16x16x32_bf16 v[12:15], v[184:187], v[216:219], v[12:15]
	s_setprio 0
	s_barrier
	s_add_i32 s54, 0, 0x18000
	s_add_i32 s55, 0, 0x1c000
	v_add_u32_e32 v132, s54, v178
	v_add_u32_e32 v183, s55, v178
	ds_read_b128 v[120:123], v132
	ds_read_b128 v[124:127], v132 offset:1024
	ds_read_b128 v[128:131], v132 offset:2048
	ds_read_b128 v[132:135], v132 offset:3072
	ds_read_b128 v[136:139], v183
	ds_read_b128 v[140:143], v183 offset:1024
	ds_read_b128 v[170:173], v183 offset:2048
	ds_read_b128 v[184:187], v183 offset:3072
	s_add_u32 s44, s60, 0x80000
	s_addc_u32 s45, s61, 0
	s_mov_b32 m0, s76
	v_lshl_add_u64 v[228:229], s[44:45], 0, v[152:153]
	ds_read_b128 v[188:191], v182 offset:32768
	ds_read_b128 v[192:195], v182 offset:33792
	ds_read_b128 v[196:199], v182 offset:34816
	ds_read_b128 v[200:203], v182 offset:35840
	ds_read_b128 v[204:207], v182 offset:36864
	ds_read_b128 v[208:211], v182 offset:37888
	ds_read_b128 v[212:215], v182 offset:38912
	ds_read_b128 v[216:219], v182 offset:39936
	global_load_lds_dwordx4 v[228:229], off
	v_lshl_add_u64 v[228:229], s[44:45], 0, v[156:157]
	s_mov_b32 m0, s77
	s_nop 0
	global_load_lds_dwordx4 v[228:229], off
	s_waitcnt vmcnt(8)
	s_waitcnt lgkmcnt(0)
	s_setprio 1
	s_barrier
	s_waitcnt lgkmcnt(0)
	v_mfma_f32_16x16x32_bf16 v[144:147], v[120:123], v[188:191], v[144:147]
	v_mfma_f32_16x16x32_bf16 v[60:63], v[128:131], v[188:191], v[60:63]
	v_mfma_f32_16x16x32_bf16 v[116:119], v[120:123], v[196:199], v[116:119]
	v_mfma_f32_16x16x32_bf16 v[52:55], v[128:131], v[196:199], v[52:55]
	v_mfma_f32_16x16x32_bf16 v[108:111], v[120:123], v[204:207], v[108:111]
	v_mfma_f32_16x16x32_bf16 v[44:47], v[128:131], v[204:207], v[44:47]
	v_mfma_f32_16x16x32_bf16 v[96:99], v[120:123], v[212:215], v[96:99]
	v_mfma_f32_16x16x32_bf16 v[36:39], v[128:131], v[212:215], v[36:39]
	v_mfma_f32_16x16x32_bf16 v[144:147], v[124:127], v[192:195], v[144:147]
	v_mfma_f32_16x16x32_bf16 v[60:63], v[132:135], v[192:195], v[60:63]
	v_mfma_f32_16x16x32_bf16 v[116:119], v[124:127], v[200:203], v[116:119]
	v_mfma_f32_16x16x32_bf16 v[52:55], v[132:135], v[200:203], v[52:55]
	v_mfma_f32_16x16x32_bf16 v[108:111], v[124:127], v[208:211], v[108:111]
	v_mfma_f32_16x16x32_bf16 v[44:47], v[132:135], v[208:211], v[44:47]
	v_mfma_f32_16x16x32_bf16 v[96:99], v[124:127], v[216:219], v[96:99]
	v_mfma_f32_16x16x32_bf16 v[36:39], v[132:135], v[216:219], v[36:39]
	s_setprio 0
	s_setprio 1
	v_mfma_f32_16x16x32_bf16 v[148:151], v[136:139], v[188:191], v[148:151]
	v_mfma_f32_16x16x32_bf16 v[56:59], v[170:173], v[188:191], v[56:59]
	v_mfma_f32_16x16x32_bf16 v[112:115], v[136:139], v[196:199], v[112:115]
	v_mfma_f32_16x16x32_bf16 v[48:51], v[170:173], v[196:199], v[48:51]
	v_mfma_f32_16x16x32_bf16 v[104:107], v[136:139], v[204:207], v[104:107]
	v_mfma_f32_16x16x32_bf16 v[40:43], v[170:173], v[204:207], v[40:43]
	v_mfma_f32_16x16x32_bf16 v[100:103], v[136:139], v[212:215], v[100:103]
	v_mfma_f32_16x16x32_bf16 v[32:35], v[170:173], v[212:215], v[32:35]
	v_mfma_f32_16x16x32_bf16 v[148:151], v[140:143], v[192:195], v[148:151]
	v_mfma_f32_16x16x32_bf16 v[56:59], v[184:187], v[192:195], v[56:59]
	v_mfma_f32_16x16x32_bf16 v[112:115], v[140:143], v[200:203], v[112:115]
	v_mfma_f32_16x16x32_bf16 v[48:51], v[184:187], v[200:203], v[48:51]
	v_mfma_f32_16x16x32_bf16 v[104:107], v[140:143], v[208:211], v[104:107]
	v_mfma_f32_16x16x32_bf16 v[40:43], v[184:187], v[208:211], v[40:43]
	v_mfma_f32_16x16x32_bf16 v[100:103], v[140:143], v[216:219], v[100:103]
	v_mfma_f32_16x16x32_bf16 v[32:35], v[184:187], v[216:219], v[32:35]
	s_setprio 0
	s_barrier
; #define PG8_STAGE(bufoff, gbase, voff) do { _Pragma("unroll") for (int _i = 0; _i < 2; ++_i) \
;         __builtin_amdgcn_global_load_lds((const unsigned*)((const char*)(gbase) + (voff)[_i]), (PG8_LAS unsigned*)(lds + (bufoff) + ldsw + _i * 8192), 16, 0, 0); } while (0)
; #define PG8_LDA(dst, b, h) do { _Pragma("unroll") for (int m = 0; m < 4; ++m) _Pragma("unroll") for (int k = 0; k < 2; ++k) dst[m][k] = *(const PG8_LAS bf16x8*)(lds + PG8_SA(b, h) + aoff + m * 2048 + k * 1024); } while (0)
; #define PG8_MMA(ai, bj, At, Bt) do { __builtin_amdgcn_s_setprio(1); _Pragma("unroll") for (int m = 0; m < 4; ++m) _Pragma("unroll") for (int n = 0; n < 2; ++n) _Pragma("unroll") for (int k = 0; k < 2; ++k) \
;         acc[ai][bj][m][n] = __builtin_amdgcn_mfma_f32_16x16x32_bf16(Bt[n][k], At[m][k], acc[ai][bj][m][n], 0, 0, 0); __builtin_amdgcn_s_setprio(0); } while (0)
; #define PG8_WAIT_V(n) asm volatile("s_waitcnt vmcnt(" #n ")" ::: "memory")
; #define PG8_WAIT_L(n) asm volatile("s_waitcnt lgkmcnt(" #n ")" ::: "memory")
; #define PG8_BAR __builtin_amdgcn_s_barrier()
; #define PG8_SCHED __builtin_amdgcn_sched_barrier(0)
; template <class Epi, class Sched, bool ALIGN_EPI = false, bool SP2 = false>
; __device__ __forceinline__ void gemm_phase(PG8_LAS unsigned char* lds, const Gemm g, const Sched& S, const Epi& E) {
;     ...
;         for (int t = 0; t < nt; t += 2) {
;             const bool last = (t == nt - 2);
;             const char* a1 = cA + (size_t)(t + 1) * kstep;
;             const char* a2 = last ? nA : cA + (size_t)(t + 2) * kstep; const char* b2 = last ? nB : cB + (size_t)(t + 2) * kstep;
;     ...
;             PG8_LDA(At, 1, 1); PG8_STAGE(PG8_SB(1, 0), b3, voffB); PG8_STAGE(PG8_SB(1, 1), b3 + hstep, voffB); PG8_STAGE(PG8_SA(1, 0), a3, voffA);
;             PG8_WAIT_V(8); PG8_WAIT_L(0); PG8_BAR; PG8_MMA(1, 0, At, B0); PG8_MMA(1, 1, At, B1); PG8_BAR; PG8_SCHED;
	s_add_i32 s44, s54, s67
	v_lshl_add_u64 v[220:221], v[220:221], 0, s[34:35]
	s_mov_b32 m0, s44
	ds_read_b128 v[188:191], v182 offset:49152
	ds_read_b128 v[192:195], v182 offset:50176
	ds_read_b128 v[196:199], v182 offset:51200
	ds_read_b128 v[200:203], v182 offset:52224
	ds_read_b128 v[204:207], v182 offset:53248
	ds_read_b128 v[208:211], v182 offset:54272
	ds_read_b128 v[212:215], v182 offset:55296
	ds_read_b128 v[216:219], v182 offset:56320
	global_load_lds_dwordx4 v[220:221], off
	s_add_i32 m0, s44, 0x2000
	s_add_u32 s44, s58, 0x80080
	v_lshl_add_u64 v[220:221], v[222:223], 0, s[34:35]
	s_addc_u32 s45, s59, 0
	s_add_i32 s54, s55, s67
	global_load_lds_dwordx4 v[220:221], off
	v_lshl_add_u64 v[220:221], s[44:45], 0, v[154:155]
	s_mov_b32 m0, s54
	s_nop 0
	global_load_lds_dwordx4 v[220:221], off
	v_lshl_add_u64 v[220:221], s[44:45], 0, v[158:159]
	s_add_i32 m0, s54, 0x2000
	s_nop 0
	global_load_lds_dwordx4 v[220:221], off
	v_lshl_add_u64 v[220:221], v[224:225], 0, s[34:35]
	s_mov_b32 m0, s87
	s_nop 0
	global_load_lds_dwordx4 v[220:221], off
	v_lshl_add_u64 v[220:221], v[226:227], 0, s[34:35]
	s_mov_b32 m0, s88
	s_nop 0
	global_load_lds_dwordx4 v[220:221], off
	s_waitcnt vmcnt(8)
	s_waitcnt lgkmcnt(0)
	s_setprio 1
	s_barrier
	s_waitcnt lgkmcnt(0)
	v_mfma_f32_16x16x32_bf16 v[92:95], v[120:123], v[188:191], v[92:95]
	v_mfma_f32_16x16x32_bf16 v[28:31], v[128:131], v[188:191], v[28:31]
	v_mfma_f32_16x16x32_bf16 v[84:87], v[120:123], v[196:199], v[84:87]
	v_mfma_f32_16x16x32_bf16 v[8:11], v[128:131], v[196:199], v[8:11]
	v_mfma_f32_16x16x32_bf16 v[76:79], v[120:123], v[204:207], v[76:79]
	v_mfma_f32_16x16x32_bf16 v[20:23], v[128:131], v[204:207], v[20:23]
	v_mfma_f32_16x16x32_bf16 v[68:71], v[120:123], v[212:215], v[68:71]
	v_mfma_f32_16x16x32_bf16 v[16:19], v[128:131], v[212:215], v[16:19]
	v_mfma_f32_16x16x32_bf16 v[92:95], v[124:127], v[192:195], v[92:95]
	v_mfma_f32_16x16x32_bf16 v[28:31], v[132:135], v[192:195], v[28:31]
	v_mfma_f32_16x16x32_bf16 v[84:87], v[124:127], v[200:203], v[84:87]
	v_mfma_f32_16x16x32_bf16 v[8:11], v[132:135], v[200:203], v[8:11]
	v_mfma_f32_16x16x32_bf16 v[76:79], v[124:127], v[208:211], v[76:79]
	v_mfma_f32_16x16x32_bf16 v[20:23], v[132:135], v[208:211], v[20:23]
	v_mfma_f32_16x16x32_bf16 v[68:71], v[124:127], v[216:219], v[68:71]
	v_mfma_f32_16x16x32_bf16 v[16:19], v[132:135], v[216:219], v[16:19]
	s_setprio 0
	s_setprio 1
	v_mfma_f32_16x16x32_bf16 v[88:91], v[136:139], v[188:191], v[88:91]
	v_mfma_f32_16x16x32_bf16 v[24:27], v[170:173], v[188:191], v[24:27]
	v_mfma_f32_16x16x32_bf16 v[80:83], v[136:139], v[196:199], v[80:83]
	v_mfma_f32_16x16x32_bf16 v[0:3], v[170:173], v[196:199], v[0:3]
	v_mfma_f32_16x16x32_bf16 v[72:75], v[136:139], v[204:207], v[72:75]
	v_mfma_f32_16x16x32_bf16 v[4:7], v[170:173], v[204:207], v[4:7]
	v_mfma_f32_16x16x32_bf16 v[64:67], v[136:139], v[212:215], v[64:67]
	v_mfma_f32_16x16x32_bf16 v[12:15], v[170:173], v[212:215], v[12:15]
	v_mfma_f32_16x16x32_bf16 v[88:91], v[140:143], v[192:195], v[88:91]
	v_mfma_f32_16x16x32_bf16 v[24:27], v[184:187], v[192:195], v[24:27]
	v_mfma_f32_16x16x32_bf16 v[80:83], v[140:143], v[200:203], v[80:83]
	v_mfma_f32_16x16x32_bf16 v[0:3], v[184:187], v[200:203], v[0:3]
	v_mfma_f32_16x16x32_bf16 v[72:75], v[140:143], v[208:211], v[72:75]
	v_mfma_f32_16x16x32_bf16 v[4:7], v[184:187], v[208:211], v[4:7]
	v_mfma_f32_16x16x32_bf16 v[64:67], v[140:143], v[216:219], v[64:67]
	v_mfma_f32_16x16x32_bf16 v[12:15], v[184:187], v[216:219], v[12:15]
	s_setprio 0
	s_barrier
	s_add_i32 vcc_hi, vcc_hi, 2
	s_add_u32 s56, s56, 0x100
	s_addc_u32 s57, s57, 0
	s_add_u32 s97, s97, 0x100
	s_addc_u32 vcc_lo, vcc_lo, 0
	s_cmp_gt_u32 vcc_hi, 29
	s_cbranch_scc0 .LBB0_671
	s_and_b64 vcc, exec, s[38:39]
	s_cbranch_vccz .LBB0_674
	s_barrier

; #define PG8_STAGE(bufoff, gbase, voff) do { _Pragma("unroll") for (int _i = 0; _i < 2; ++_i) \
;         __builtin_amdgcn_global_load_lds((const unsigned*)((const char*)(gbase) + (voff)[_i]), (PG8_LAS unsigned*)(lds + (bufoff) + ldsw + _i * 8192), 16, 0, 0); } while (0)
; #define PG8_LDA(dst, b, h) do { _Pragma("unroll") for (int m = 0; m < 4; ++m) _Pragma("unroll") for (int k = 0; k < 2; ++k) dst[m][k] = *(const PG8_LAS bf16x8*)(lds + PG8_SA(b, h) + aoff + m * 2048 + k * 1024); } while (0)
; #define PG8_LDB(dst, b, h) do { _Pragma("unroll") for (int n = 0; n < 2; ++n) _Pragma("unroll") for (int k = 0; k < 2; ++k) dst[n][k] = *(const PG8_LAS bf16x8*)(lds + PG8_SB(b, h) + boff + n * 2048 + k * 1024); } while (0)
; #define PG8_MMA(ai, bj, At, Bt) do { __builtin_amdgcn_s_setprio(1); _Pragma("unroll") for (int m = 0; m < 4; ++m) _Pragma("unroll") for (int n = 0; n < 2; ++n) _Pragma("unroll") for (int k = 0; k < 2; ++k) \
;         acc[ai][bj][m][n] = __builtin_amdgcn_mfma_f32_16x16x32_bf16(Bt[n][k], At[m][k], acc[ai][bj][m][n], 0, 0, 0); __builtin_amdgcn_s_setprio(0); } while (0)
; #define PG8_WAIT_V(n) asm volatile("s_waitcnt vmcnt(" #n ")" ::: "memory")
; #define PG8_BAR __builtin_amdgcn_s_barrier()
; template <class Epi, class Sched, bool ALIGN_EPI = false, bool SP2 = false>
; __device__ __forceinline__ void gemm_phase(PG8_LAS unsigned char* lds, const Gemm g, const Sched& S, const Epi& E) {
;     ...
;         for (int t = 0; t < nt; t += 2) {
;             const bool last = (t == nt - 2);
;             const char* a1 = cA + (size_t)(t + 1) * kstep;
;             const char* a2 = last ? nA : cA + (size_t)(t + 2) * kstep; const char* b2 = last ? nB : cB + (size_t)(t + 2) * kstep;
;             const char* a3 = a2 + kstep; const char* b3 = b2 + kstep;
;             if (last && has_next) S.a_ready(nxt);
;             if constexpr (SP2) {
;             PG8_LDB(B0, 0, 0); PG8_LDB(B1, 0, 1); PG8_SCHED; PG8_LDA(At, 0, 0); PG8_STAGE(PG8_SA(1, 1), a1 + hstep, voffA);
;             PG8_WAIT_V(8); PG8_WAIT_L(0); PG8_BAR; PG8_MMA(0, 0, At, B0); PG8_MMA(0, 1, At, B1); PG8_BAR; PG8_SCHED;
;             PG8_LDA(At, 0, 1); PG8_STAGE(PG8_SB(0, 0), b2, voffB); PG8_STAGE(PG8_SB(0, 1), b2 + hstep, voffB); PG8_STAGE(PG8_SA(0, 0), a2, voffA);
;             PG8_WAIT_V(8); PG8_WAIT_L(0); PG8_BAR; PG8_MMA(1, 0, At, B0); PG8_MMA(1, 1, At, B1); PG8_BAR; PG8_SCHED;
.LBB0_828:
	ds_read_b128 v[152:155], v149
	ds_read_b128 v[156:159], v149 offset:1024
	ds_read_b128 v[160:163], v149 offset:2048
	ds_read_b128 v[164:167], v149 offset:3072
	ds_read_b128 v[168:171], v150
	ds_read_b128 v[176:179], v150 offset:1024
	ds_read_b128 v[180:183], v150 offset:2048
	ds_read_b128 v[184:187], v150 offset:3072
	s_add_u32 s30, s28, 0xffea0080
	s_addc_u32 s31, s29, -1
	s_cmpk_eq_i32 s72, 0x54
	s_cselect_b32 s35, s7, s31
	s_cselect_b32 s34, s6, s30
	s_cselect_b32 s31, s27, s69
	s_cselect_b32 s30, s26, s68
	v_lshl_add_u64 v[144:145], s[28:29], 0, v[136:137]
	s_add_i32 m0, s46, 0xc000
	ds_read_b128 v[188:191], v151
	ds_read_b128 v[192:195], v151 offset:1024
	ds_read_b128 v[196:199], v151 offset:2048
	ds_read_b128 v[200:203], v151 offset:3072
	ds_read_b128 v[204:207], v151 offset:4096
	ds_read_b128 v[208:211], v151 offset:5120
	ds_read_b128 v[212:215], v151 offset:6144
	ds_read_b128 v[216:219], v151 offset:7168
	global_load_lds_dwordx4 v[144:145], off
	v_lshl_add_u64 v[144:145], s[28:29], 0, v[138:139]
	s_add_i32 m0, s46, 0xe000
	s_nop 0
	global_load_lds_dwordx4 v[144:145], off
	s_waitcnt vmcnt(8)
	s_waitcnt lgkmcnt(0)
	s_setprio 1
	s_barrier
	s_waitcnt lgkmcnt(0)
	v_mfma_f32_16x16x32_bf16 v[124:127], v[152:155], v[188:191], v[124:127]
	v_mfma_f32_16x16x32_bf16 v[120:123], v[160:163], v[188:191], v[120:123]
	v_mfma_f32_16x16x32_bf16 v[116:119], v[152:155], v[196:199], v[116:119]
	v_mfma_f32_16x16x32_bf16 v[108:111], v[160:163], v[196:199], v[108:111]
	v_mfma_f32_16x16x32_bf16 v[100:103], v[152:155], v[204:207], v[100:103]
	v_mfma_f32_16x16x32_bf16 v[92:95], v[160:163], v[204:207], v[92:95]
	v_mfma_f32_16x16x32_bf16 v[84:87], v[152:155], v[212:215], v[84:87]
	v_mfma_f32_16x16x32_bf16 v[76:79], v[160:163], v[212:215], v[76:79]
	v_mfma_f32_16x16x32_bf16 v[124:127], v[156:159], v[192:195], v[124:127]
	v_mfma_f32_16x16x32_bf16 v[120:123], v[164:167], v[192:195], v[120:123]
	v_mfma_f32_16x16x32_bf16 v[116:119], v[156:159], v[200:203], v[116:119]
	v_mfma_f32_16x16x32_bf16 v[108:111], v[164:167], v[200:203], v[108:111]
	v_mfma_f32_16x16x32_bf16 v[100:103], v[156:159], v[208:211], v[100:103]
	v_mfma_f32_16x16x32_bf16 v[92:95], v[164:167], v[208:211], v[92:95]
	v_mfma_f32_16x16x32_bf16 v[84:87], v[156:159], v[216:219], v[84:87]
	v_mfma_f32_16x16x32_bf16 v[76:79], v[164:167], v[216:219], v[76:79]
	s_setprio 0
	s_setprio 1
	v_mfma_f32_16x16x32_bf16 v[112:115], v[168:171], v[188:191], v[112:115]
	v_mfma_f32_16x16x32_bf16 v[104:107], v[180:183], v[188:191], v[104:107]
	v_mfma_f32_16x16x32_bf16 v[96:99], v[168:171], v[196:199], v[96:99]
	v_mfma_f32_16x16x32_bf16 v[88:91], v[180:183], v[196:199], v[88:91]
	v_mfma_f32_16x16x32_bf16 v[80:83], v[168:171], v[204:207], v[80:83]
	v_mfma_f32_16x16x32_bf16 v[72:75], v[180:183], v[204:207], v[72:75]
	v_mfma_f32_16x16x32_bf16 v[68:71], v[168:171], v[212:215], v[68:71]
	v_mfma_f32_16x16x32_bf16 v[64:67], v[180:183], v[212:215], v[64:67]
	v_mfma_f32_16x16x32_bf16 v[112:115], v[176:179], v[192:195], v[112:115]
	v_mfma_f32_16x16x32_bf16 v[104:107], v[184:187], v[192:195], v[104:107]
	v_mfma_f32_16x16x32_bf16 v[96:99], v[176:179], v[200:203], v[96:99]
	v_mfma_f32_16x16x32_bf16 v[88:91], v[184:187], v[200:203], v[88:91]
	v_mfma_f32_16x16x32_bf16 v[80:83], v[176:179], v[208:211], v[80:83]
	v_mfma_f32_16x16x32_bf16 v[72:75], v[184:187], v[208:211], v[72:75]
	v_mfma_f32_16x16x32_bf16 v[68:71], v[176:179], v[216:219], v[68:71]
	v_mfma_f32_16x16x32_bf16 v[64:67], v[184:187], v[216:219], v[64:67]
	s_setprio 0
	s_barrier
	s_add_i32 s44, s57, s42
	v_lshl_add_u64 v[144:145], s[30:31], 0, v[130:131]
	s_mov_b32 m0, s44
	ds_read_b128 v[188:191], v151 offset:16384
	ds_read_b128 v[192:195], v151 offset:17408
	ds_read_b128 v[196:199], v151 offset:18432
	ds_read_b128 v[200:203], v151 offset:19456
	ds_read_b128 v[204:207], v151 offset:20480
	ds_read_b128 v[208:211], v151 offset:21504
	ds_read_b128 v[212:215], v151 offset:22528
	ds_read_b128 v[216:219], v151 offset:23552
	global_load_lds_dwordx4 v[144:145], off
	s_add_i32 m0, s44, 0x2000
	s_add_u32 s44, s30, 0x160000
	v_lshl_add_u64 v[172:173], s[30:31], 0, v[134:135]
	s_addc_u32 s45, s31, 0
	s_add_i32 s54, s58, s42
	global_load_lds_dwordx4 v[172:173], off
	v_lshl_add_u64 v[220:221], s[44:45], 0, v[130:131]
	s_mov_b32 m0, s54
	v_lshl_add_u64 v[222:223], s[34:35], 0, v[132:133]
	global_load_lds_dwordx4 v[220:221], off
	v_lshl_add_u64 v[220:221], s[44:45], 0, v[134:135]
	s_add_i32 m0, s54, 0x2000
	s_nop 0
	global_load_lds_dwordx4 v[220:221], off
	v_lshl_add_u64 v[220:221], s[34:35], 0, v[128:129]
	s_mov_b32 m0, s46
	s_nop 0
	global_load_lds_dwordx4 v[220:221], off
	s_mov_b32 m0, s47
	s_nop 0
	global_load_lds_dwordx4 v[222:223], off
	s_waitcnt vmcnt(8)
	s_waitcnt lgkmcnt(0)
	s_setprio 1
	s_barrier
; #define PG8_STAGE(bufoff, gbase, voff) do { _Pragma("unroll") for (int _i = 0; _i < 2; ++_i) \
;         __builtin_amdgcn_global_load_lds((const unsigned*)((const char*)(gbase) + (voff)[_i]), (PG8_LAS unsigned*)(lds + (bufoff) + ldsw + _i * 8192), 16, 0, 0); } while (0)
; #define PG8_LDA(dst, b, h) do { _Pragma("unroll") for (int m = 0; m < 4; ++m) _Pragma("unroll") for (int k = 0; k < 2; ++k) dst[m][k] = *(const PG8_LAS bf16x8*)(lds + PG8_SA(b, h) + aoff + m * 2048 + k * 1024); } while (0)
; #define PG8_LDB(dst, b, h) do { _Pragma("unroll") for (int n = 0; n < 2; ++n) _Pragma("unroll") for (int k = 0; k < 2; ++k) dst[n][k] = *(const PG8_LAS bf16x8*)(lds + PG8_SB(b, h) + boff + n * 2048 + k * 1024); } while (0)
; #define PG8_MMA(ai, bj, At, Bt) do { __builtin_amdgcn_s_setprio(1); _Pragma("unroll") for (int m = 0; m < 4; ++m) _Pragma("unroll") for (int n = 0; n < 2; ++n) _Pragma("unroll") for (int k = 0; k < 2; ++k) \
;         acc[ai][bj][m][n] = __builtin_amdgcn_mfma_f32_16x16x32_bf16(Bt[n][k], At[m][k], acc[ai][bj][m][n], 0, 0, 0); __builtin_amdgcn_s_setprio(0); } while (0)
; #define PG8_WAIT_V(n) asm volatile("s_waitcnt vmcnt(" #n ")" ::: "memory")
; #define PG8_WAIT_L(n) asm volatile("s_waitcnt lgkmcnt(" #n ")" ::: "memory")
; #define PG8_BAR __builtin_amdgcn_s_barrier()
; #define PG8_SCHED __builtin_amdgcn_sched_barrier(0)
; template <class Epi, class Sched, bool ALIGN_EPI = false, bool SP2 = false>
; __device__ __forceinline__ void gemm_phase(PG8_LAS unsigned char* lds, const Gemm g, const Sched& S, const Epi& E) {
;     ...
;             PG8_WAIT_V(8); PG8_WAIT_L(0); PG8_BAR; PG8_MMA(1, 0, At, B0); PG8_MMA(1, 1, At, B1); PG8_BAR; PG8_SCHED;
;             PG8_LDB(B0, 1, 0); PG8_LDB(B1, 1, 1); PG8_SCHED; PG8_LDA(At, 1, 0); PG8_STAGE(PG8_SA(0, 1), a2 + hstep, voffA);
;             PG8_WAIT_V(8); PG8_WAIT_L(0); PG8_BAR; PG8_MMA(0, 0, At, B0); PG8_MMA(0, 1, At, B1); PG8_BAR; PG8_SCHED;
	s_waitcnt lgkmcnt(0)
	v_mfma_f32_16x16x32_bf16 v[60:63], v[152:155], v[188:191], v[60:63]
	v_mfma_f32_16x16x32_bf16 v[56:59], v[160:163], v[188:191], v[56:59]
	v_mfma_f32_16x16x32_bf16 v[52:55], v[152:155], v[196:199], v[52:55]
	v_mfma_f32_16x16x32_bf16 v[44:47], v[160:163], v[196:199], v[44:47]
	v_mfma_f32_16x16x32_bf16 v[36:39], v[152:155], v[204:207], v[36:39]
	v_mfma_f32_16x16x32_bf16 v[28:31], v[160:163], v[204:207], v[28:31]
	v_mfma_f32_16x16x32_bf16 v[20:23], v[152:155], v[212:215], v[20:23]
	v_mfma_f32_16x16x32_bf16 v[12:15], v[160:163], v[212:215], v[12:15]
	v_mfma_f32_16x16x32_bf16 v[60:63], v[156:159], v[192:195], v[60:63]
	v_mfma_f32_16x16x32_bf16 v[56:59], v[164:167], v[192:195], v[56:59]
	v_mfma_f32_16x16x32_bf16 v[52:55], v[156:159], v[200:203], v[52:55]
	v_mfma_f32_16x16x32_bf16 v[44:47], v[164:167], v[200:203], v[44:47]
	v_mfma_f32_16x16x32_bf16 v[36:39], v[156:159], v[208:211], v[36:39]
	v_mfma_f32_16x16x32_bf16 v[28:31], v[164:167], v[208:211], v[28:31]
	v_mfma_f32_16x16x32_bf16 v[20:23], v[156:159], v[216:219], v[20:23]
	v_mfma_f32_16x16x32_bf16 v[12:15], v[164:167], v[216:219], v[12:15]
	s_setprio 0
	s_setprio 1
	v_mfma_f32_16x16x32_bf16 v[48:51], v[168:171], v[188:191], v[48:51]
	v_mfma_f32_16x16x32_bf16 v[40:43], v[180:183], v[188:191], v[40:43]
	v_mfma_f32_16x16x32_bf16 v[32:35], v[168:171], v[196:199], v[32:35]
	v_mfma_f32_16x16x32_bf16 v[24:27], v[180:183], v[196:199], v[24:27]
	v_mfma_f32_16x16x32_bf16 v[16:19], v[168:171], v[204:207], v[16:19]
	v_mfma_f32_16x16x32_bf16 v[8:11], v[180:183], v[204:207], v[8:11]
	v_mfma_f32_16x16x32_bf16 v[4:7], v[168:171], v[212:215], v[4:7]
	v_mfma_f32_16x16x32_bf16 v[0:3], v[180:183], v[212:215], v[0:3]
	v_mfma_f32_16x16x32_bf16 v[48:51], v[176:179], v[192:195], v[48:51]
	v_mfma_f32_16x16x32_bf16 v[40:43], v[184:187], v[192:195], v[40:43]
	v_mfma_f32_16x16x32_bf16 v[32:35], v[176:179], v[200:203], v[32:35]
	v_mfma_f32_16x16x32_bf16 v[24:27], v[184:187], v[200:203], v[24:27]
	v_mfma_f32_16x16x32_bf16 v[16:19], v[176:179], v[208:211], v[16:19]
	v_mfma_f32_16x16x32_bf16 v[8:11], v[184:187], v[208:211], v[8:11]
	v_mfma_f32_16x16x32_bf16 v[4:7], v[176:179], v[216:219], v[4:7]
	v_mfma_f32_16x16x32_bf16 v[0:3], v[184:187], v[216:219], v[0:3]
	s_setprio 0
	s_barrier
	s_add_i32 s44, 0, 0x18000
	s_add_i32 s45, 0, 0x1c000
	v_add_u32_e32 v164, s44, v147
	v_add_u32_e32 v175, s45, v147
	ds_read_b128 v[152:155], v164
	ds_read_b128 v[156:159], v164 offset:1024
	ds_read_b128 v[160:163], v164 offset:2048
	ds_read_b128 v[164:167], v164 offset:3072
	ds_read_b128 v[168:171], v175
	ds_read_b128 v[176:179], v175 offset:1024
	ds_read_b128 v[180:183], v175 offset:2048
	ds_read_b128 v[184:187], v175 offset:3072
	s_add_u32 s34, s34, 0x160000
	s_addc_u32 s35, s35, 0
	s_mov_b32 m0, s48
	v_lshl_add_u64 v[224:225], s[34:35], 0, v[128:129]
	ds_read_b128 v[188:191], v151 offset:32768
	ds_read_b128 v[192:195], v151 offset:33792
	ds_read_b128 v[196:199], v151 offset:34816
	ds_read_b128 v[200:203], v151 offset:35840
	ds_read_b128 v[204:207], v151 offset:36864
	ds_read_b128 v[208:211], v151 offset:37888
	ds_read_b128 v[212:215], v151 offset:38912
	ds_read_b128 v[216:219], v151 offset:39936
	global_load_lds_dwordx4 v[224:225], off
	v_lshl_add_u64 v[224:225], s[34:35], 0, v[132:133]
	s_mov_b32 m0, s49
	s_nop 0
	global_load_lds_dwordx4 v[224:225], off
	s_waitcnt vmcnt(8)
	s_waitcnt lgkmcnt(0)
	s_setprio 1
	s_barrier
	s_waitcnt lgkmcnt(0)
	v_mfma_f32_16x16x32_bf16 v[124:127], v[152:155], v[188:191], v[124:127]
	v_mfma_f32_16x16x32_bf16 v[120:123], v[160:163], v[188:191], v[120:123]
	v_mfma_f32_16x16x32_bf16 v[116:119], v[152:155], v[196:199], v[116:119]
	v_mfma_f32_16x16x32_bf16 v[108:111], v[160:163], v[196:199], v[108:111]
	v_mfma_f32_16x16x32_bf16 v[100:103], v[152:155], v[204:207], v[100:103]
	v_mfma_f32_16x16x32_bf16 v[92:95], v[160:163], v[204:207], v[92:95]
	v_mfma_f32_16x16x32_bf16 v[84:87], v[152:155], v[212:215], v[84:87]
	v_mfma_f32_16x16x32_bf16 v[76:79], v[160:163], v[212:215], v[76:79]
	v_mfma_f32_16x16x32_bf16 v[124:127], v[156:159], v[192:195], v[124:127]
	v_mfma_f32_16x16x32_bf16 v[120:123], v[164:167], v[192:195], v[120:123]
	v_mfma_f32_16x16x32_bf16 v[116:119], v[156:159], v[200:203], v[116:119]
	v_mfma_f32_16x16x32_bf16 v[108:111], v[164:167], v[200:203], v[108:111]
	v_mfma_f32_16x16x32_bf16 v[100:103], v[156:159], v[208:211], v[100:103]
	v_mfma_f32_16x16x32_bf16 v[92:95], v[164:167], v[208:211], v[92:95]
	v_mfma_f32_16x16x32_bf16 v[84:87], v[156:159], v[216:219], v[84:87]
	v_mfma_f32_16x16x32_bf16 v[76:79], v[164:167], v[216:219], v[76:79]
	s_setprio 0
	s_setprio 1
	v_mfma_f32_16x16x32_bf16 v[112:115], v[168:171], v[188:191], v[112:115]
	v_mfma_f32_16x16x32_bf16 v[104:107], v[180:183], v[188:191], v[104:107]
	v_mfma_f32_16x16x32_bf16 v[96:99], v[168:171], v[196:199], v[96:99]
	v_mfma_f32_16x16x32_bf16 v[88:91], v[180:183], v[196:199], v[88:91]
	v_mfma_f32_16x16x32_bf16 v[80:83], v[168:171], v[204:207], v[80:83]
	v_mfma_f32_16x16x32_bf16 v[72:75], v[180:183], v[204:207], v[72:75]
	v_mfma_f32_16x16x32_bf16 v[68:71], v[168:171], v[212:215], v[68:71]
	v_mfma_f32_16x16x32_bf16 v[64:67], v[180:183], v[212:215], v[64:67]
	v_mfma_f32_16x16x32_bf16 v[112:115], v[176:179], v[192:195], v[112:115]
	v_mfma_f32_16x16x32_bf16 v[104:107], v[184:187], v[192:195], v[104:107]
	v_mfma_f32_16x16x32_bf16 v[96:99], v[176:179], v[200:203], v[96:99]
	v_mfma_f32_16x16x32_bf16 v[88:91], v[184:187], v[200:203], v[88:91]
	v_mfma_f32_16x16x32_bf16 v[80:83], v[176:179], v[208:211], v[80:83]
	v_mfma_f32_16x16x32_bf16 v[72:75], v[184:187], v[208:211], v[72:75]
	v_mfma_f32_16x16x32_bf16 v[68:71], v[176:179], v[216:219], v[68:71]
	v_mfma_f32_16x16x32_bf16 v[64:67], v[184:187], v[216:219], v[64:67]
	s_setprio 0
	s_barrier
; #define PG8_STAGE(bufoff, gbase, voff) do { _Pragma("unroll") for (int _i = 0; _i < 2; ++_i) \
;         __builtin_amdgcn_global_load_lds((const unsigned*)((const char*)(gbase) + (voff)[_i]), (PG8_LAS unsigned*)(lds + (bufoff) + ldsw + _i * 8192), 16, 0, 0); } while (0)
; #define PG8_LDA(dst, b, h) do { _Pragma("unroll") for (int m = 0; m < 4; ++m) _Pragma("unroll") for (int k = 0; k < 2; ++k) dst[m][k] = *(const PG8_LAS bf16x8*)(lds + PG8_SA(b, h) + aoff + m * 2048 + k * 1024); } while (0)
; #define PG8_MMA(ai, bj, At, Bt) do { __builtin_amdgcn_s_setprio(1); _Pragma("unroll") for (int m = 0; m < 4; ++m) _Pragma("unroll") for (int n = 0; n < 2; ++n) _Pragma("unroll") for (int k = 0; k < 2; ++k) \
;         acc[ai][bj][m][n] = __builtin_amdgcn_mfma_f32_16x16x32_bf16(Bt[n][k], At[m][k], acc[ai][bj][m][n], 0, 0, 0); __builtin_amdgcn_s_setprio(0); } while (0)
; #define PG8_WAIT_V(n) asm volatile("s_waitcnt vmcnt(" #n ")" ::: "memory")
; #define PG8_WAIT_L(n) asm volatile("s_waitcnt lgkmcnt(" #n ")" ::: "memory")
; #define PG8_BAR __builtin_amdgcn_s_barrier()
; #define PG8_SCHED __builtin_amdgcn_sched_barrier(0)
; template <class Epi, class Sched, bool ALIGN_EPI = false, bool SP2 = false>
; __device__ __forceinline__ void gemm_phase(PG8_LAS unsigned char* lds, const Gemm g, const Sched& S, const Epi& E) {
;     ...
;         for (int t = 0; t < nt; t += 2) {
;             const bool last = (t == nt - 2);
;             const char* a1 = cA + (size_t)(t + 1) * kstep;
;             const char* a2 = last ? nA : cA + (size_t)(t + 2) * kstep; const char* b2 = last ? nB : cB + (size_t)(t + 2) * kstep;
;     ...
;             PG8_LDA(At, 1, 1); PG8_STAGE(PG8_SB(1, 0), b3, voffB); PG8_STAGE(PG8_SB(1, 1), b3 + hstep, voffB); PG8_STAGE(PG8_SA(1, 0), a3, voffA);
;             PG8_WAIT_V(8); PG8_WAIT_L(0); PG8_BAR; PG8_MMA(1, 0, At, B0); PG8_MMA(1, 1, At, B1); PG8_BAR; PG8_SCHED;
	s_add_i32 s34, s44, s42
	v_lshl_add_u64 v[144:145], v[144:145], 0, s[14:15]
	s_mov_b32 m0, s34
	ds_read_b128 v[188:191], v151 offset:49152
	ds_read_b128 v[192:195], v151 offset:50176
	ds_read_b128 v[196:199], v151 offset:51200
	ds_read_b128 v[200:203], v151 offset:52224
	ds_read_b128 v[204:207], v151 offset:53248
	ds_read_b128 v[208:211], v151 offset:54272
	ds_read_b128 v[212:215], v151 offset:55296
	ds_read_b128 v[216:219], v151 offset:56320
	global_load_lds_dwordx4 v[144:145], off
	s_add_i32 m0, s34, 0x2000
	s_add_u32 s30, s30, 0x160080
	v_lshl_add_u64 v[144:145], v[172:173], 0, s[14:15]
	s_addc_u32 s31, s31, 0
	s_add_i32 s34, s45, s42
	global_load_lds_dwordx4 v[144:145], off
	v_lshl_add_u64 v[144:145], s[30:31], 0, v[130:131]
	s_mov_b32 m0, s34
	s_nop 0
	global_load_lds_dwordx4 v[144:145], off
	v_lshl_add_u64 v[144:145], s[30:31], 0, v[134:135]
	s_add_i32 m0, s34, 0x2000
	s_nop 0
	global_load_lds_dwordx4 v[144:145], off
	v_lshl_add_u64 v[144:145], v[220:221], 0, s[14:15]
	s_mov_b32 m0, s53
	s_nop 0
	global_load_lds_dwordx4 v[144:145], off
	v_lshl_add_u64 v[144:145], v[222:223], 0, s[14:15]
	s_mov_b32 m0, s56
	s_nop 0
	global_load_lds_dwordx4 v[144:145], off
	s_waitcnt vmcnt(8)
	s_waitcnt lgkmcnt(0)
	s_setprio 1
	s_barrier
	s_waitcnt lgkmcnt(0)
	v_mfma_f32_16x16x32_bf16 v[60:63], v[152:155], v[188:191], v[60:63]
	v_mfma_f32_16x16x32_bf16 v[56:59], v[160:163], v[188:191], v[56:59]
	v_mfma_f32_16x16x32_bf16 v[52:55], v[152:155], v[196:199], v[52:55]
	v_mfma_f32_16x16x32_bf16 v[44:47], v[160:163], v[196:199], v[44:47]
	v_mfma_f32_16x16x32_bf16 v[36:39], v[152:155], v[204:207], v[36:39]
	v_mfma_f32_16x16x32_bf16 v[28:31], v[160:163], v[204:207], v[28:31]
	v_mfma_f32_16x16x32_bf16 v[20:23], v[152:155], v[212:215], v[20:23]
	v_mfma_f32_16x16x32_bf16 v[12:15], v[160:163], v[212:215], v[12:15]
	v_mfma_f32_16x16x32_bf16 v[60:63], v[156:159], v[192:195], v[60:63]
	v_mfma_f32_16x16x32_bf16 v[56:59], v[164:167], v[192:195], v[56:59]
	v_mfma_f32_16x16x32_bf16 v[52:55], v[156:159], v[200:203], v[52:55]
	v_mfma_f32_16x16x32_bf16 v[44:47], v[164:167], v[200:203], v[44:47]
	v_mfma_f32_16x16x32_bf16 v[36:39], v[156:159], v[208:211], v[36:39]
	v_mfma_f32_16x16x32_bf16 v[28:31], v[164:167], v[208:211], v[28:31]
	v_mfma_f32_16x16x32_bf16 v[20:23], v[156:159], v[216:219], v[20:23]
	v_mfma_f32_16x16x32_bf16 v[12:15], v[164:167], v[216:219], v[12:15]
	s_setprio 0
	s_setprio 1
	v_mfma_f32_16x16x32_bf16 v[48:51], v[168:171], v[188:191], v[48:51]
	v_mfma_f32_16x16x32_bf16 v[40:43], v[180:183], v[188:191], v[40:43]
	v_mfma_f32_16x16x32_bf16 v[32:35], v[168:171], v[196:199], v[32:35]
	v_mfma_f32_16x16x32_bf16 v[24:27], v[180:183], v[196:199], v[24:27]
	v_mfma_f32_16x16x32_bf16 v[16:19], v[168:171], v[204:207], v[16:19]
	v_mfma_f32_16x16x32_bf16 v[8:11], v[180:183], v[204:207], v[8:11]
	v_mfma_f32_16x16x32_bf16 v[4:7], v[168:171], v[212:215], v[4:7]
	v_mfma_f32_16x16x32_bf16 v[0:3], v[180:183], v[212:215], v[0:3]
	v_mfma_f32_16x16x32_bf16 v[48:51], v[176:179], v[192:195], v[48:51]
	v_mfma_f32_16x16x32_bf16 v[40:43], v[184:187], v[192:195], v[40:43]
	v_mfma_f32_16x16x32_bf16 v[32:35], v[176:179], v[200:203], v[32:35]
	v_mfma_f32_16x16x32_bf16 v[24:27], v[184:187], v[200:203], v[24:27]
	v_mfma_f32_16x16x32_bf16 v[16:19], v[176:179], v[208:211], v[16:19]
	v_mfma_f32_16x16x32_bf16 v[8:11], v[184:187], v[208:211], v[8:11]
	v_mfma_f32_16x16x32_bf16 v[4:7], v[176:179], v[216:219], v[4:7]
	v_mfma_f32_16x16x32_bf16 v[0:3], v[184:187], v[216:219], v[0:3]
	s_setprio 0
	s_barrier
	s_add_i32 s72, s72, 2
	s_add_u32 s28, s28, 0x100
	s_addc_u32 s29, s29, 0
	s_add_u32 s68, s68, 0x100
	s_addc_u32 s69, s69, 0
	s_cmpk_gt_u32 s72, 0x55
	s_cbranch_scc0 .LBB0_828
	s_and_b64 vcc, exec, s[16:17]
	s_cbranch_vccz .LBB0_831
	s_barrier
